# prioglue
# speedup vs baseline: 1.0108x; 1.0108x over previous
.LBB0_251:
	s_add_u32 s62, s60, 0xfff80080
	s_addc_u32 s63, s61, -1
	s_add_i32 s78, 0, 0x10000
	s_cmp_eq_u32 s77, 28
	s_cselect_b32 s65, s26, s63
	s_cselect_b32 s64, s47, s62
	v_add_u32_e32 v0, s78, v143
	s_cselect_b32 s63, s45, s76
	s_cselect_b32 s62, s72, s73
	s_add_i32 s80, 0, 0x14000
	ds_read_b128 v[146:149], v0
	ds_read_b128 v[150:153], v0 offset:1024
	ds_read_b128 v[154:157], v0 offset:2048
	ds_read_b128 v[158:161], v0 offset:3072
	v_add_u32_e32 v0, s80, v143
	ds_read_b128 v[162:165], v0
	ds_read_b128 v[176:179], v0 offset:1024
	ds_read_b128 v[180:183], v0 offset:2048
	ds_read_b128 v[184:187], v0 offset:3072
	v_lshl_add_u64 v[140:141], s[60:61], 0, v[138:139]
	s_add_i32 m0, s22, 0xc000
	ds_read_b128 v[188:191], v144
	ds_read_b128 v[192:195], v144 offset:1024
	ds_read_b128 v[196:199], v144 offset:2048
	ds_read_b128 v[200:203], v144 offset:3072
	ds_read_b128 v[204:207], v144 offset:4096
	ds_read_b128 v[208:211], v144 offset:5120
	ds_read_b128 v[224:227], v144 offset:6144
	ds_read_b128 v[228:231], v144 offset:7168
	global_load_lds_dwordx4 v[140:141], off
	v_lshl_add_u64 v[140:141], s[60:61], 0, v[136:137]
	s_add_i32 m0, s22, 0xe000
	s_nop 0
	global_load_lds_dwordx4 v[140:141], off
	s_waitcnt vmcnt(8)
	s_waitcnt lgkmcnt(0)
	s_barrier
	s_setprio 1
	s_waitcnt lgkmcnt(0)
	v_mfma_f32_16x16x32_bf16 v[126:129], v[146:149], v[188:191], v[126:129]
	v_mfma_f32_16x16x32_bf16 v[122:125], v[154:157], v[188:191], v[122:125]
	v_mfma_f32_16x16x32_bf16 v[114:117], v[146:149], v[196:199], v[114:117]
	v_mfma_f32_16x16x32_bf16 v[106:109], v[154:157], v[196:199], v[106:109]
	v_mfma_f32_16x16x32_bf16 v[98:101], v[146:149], v[204:207], v[98:101]
	v_mfma_f32_16x16x32_bf16 v[90:93], v[154:157], v[204:207], v[90:93]
	v_mfma_f32_16x16x32_bf16 v[82:85], v[146:149], v[224:227], v[82:85]
	v_mfma_f32_16x16x32_bf16 v[74:77], v[154:157], v[224:227], v[74:77]
	v_mfma_f32_16x16x32_bf16 v[126:129], v[150:153], v[192:195], v[126:129]
	v_mfma_f32_16x16x32_bf16 v[122:125], v[158:161], v[192:195], v[122:125]
	v_mfma_f32_16x16x32_bf16 v[114:117], v[150:153], v[200:203], v[114:117]
	v_mfma_f32_16x16x32_bf16 v[106:109], v[158:161], v[200:203], v[106:109]
	v_mfma_f32_16x16x32_bf16 v[98:101], v[150:153], v[208:211], v[98:101]
	v_mfma_f32_16x16x32_bf16 v[90:93], v[158:161], v[208:211], v[90:93]
	v_mfma_f32_16x16x32_bf16 v[82:85], v[150:153], v[228:231], v[82:85]
	v_mfma_f32_16x16x32_bf16 v[74:77], v[158:161], v[228:231], v[74:77]
	v_mfma_f32_16x16x32_bf16 v[118:121], v[162:165], v[188:191], v[118:121]
	v_mfma_f32_16x16x32_bf16 v[110:113], v[180:183], v[188:191], v[110:113]
	v_mfma_f32_16x16x32_bf16 v[102:105], v[162:165], v[196:199], v[102:105]
	v_mfma_f32_16x16x32_bf16 v[94:97], v[180:183], v[196:199], v[94:97]
	v_mfma_f32_16x16x32_bf16 v[86:89], v[162:165], v[204:207], v[86:89]
	v_mfma_f32_16x16x32_bf16 v[78:81], v[180:183], v[204:207], v[78:81]
	v_mfma_f32_16x16x32_bf16 v[70:73], v[162:165], v[224:227], v[70:73]
	v_mfma_f32_16x16x32_bf16 v[66:69], v[180:183], v[224:227], v[66:69]
	v_mfma_f32_16x16x32_bf16 v[118:121], v[176:179], v[192:195], v[118:121]
	v_mfma_f32_16x16x32_bf16 v[110:113], v[184:187], v[192:195], v[110:113]
	v_mfma_f32_16x16x32_bf16 v[102:105], v[176:179], v[200:203], v[102:105]
	v_mfma_f32_16x16x32_bf16 v[94:97], v[184:187], v[200:203], v[94:97]
	v_mfma_f32_16x16x32_bf16 v[86:89], v[176:179], v[208:211], v[86:89]
	v_mfma_f32_16x16x32_bf16 v[78:81], v[184:187], v[208:211], v[78:81]
	v_mfma_f32_16x16x32_bf16 v[70:73], v[176:179], v[228:231], v[70:73]
	v_mfma_f32_16x16x32_bf16 v[66:69], v[184:187], v[228:231], v[66:69]
	s_setprio 0
	s_barrier
	s_add_i32 s78, s78, s14
	v_lshl_add_u64 v[140:141], s[62:63], 0, v[132:133]
	s_mov_b32 m0, s78
	ds_read_b128 v[188:191], v144 offset:16384
	ds_read_b128 v[192:195], v144 offset:17408
	ds_read_b128 v[196:199], v144 offset:18432
	ds_read_b128 v[200:203], v144 offset:19456
	ds_read_b128 v[204:207], v144 offset:20480
	ds_read_b128 v[208:211], v144 offset:21504
	ds_read_b128 v[224:227], v144 offset:22528
	ds_read_b128 v[228:231], v144 offset:23552
	global_load_lds_dwordx4 v[140:141], off
	s_add_i32 m0, s78, 0x2000
	s_add_u32 s78, s62, 0x80000
	v_lshl_add_u64 v[168:169], s[62:63], 0, v[130:131]
	s_addc_u32 s79, s63, 0
	s_add_i32 s80, s80, s14
	global_load_lds_dwordx4 v[168:169], off
	v_lshl_add_u64 v[170:171], s[78:79], 0, v[132:133]
	s_mov_b32 m0, s80
	v_lshl_add_u64 v[172:173], s[64:65], 0, v[130:131]
	global_load_lds_dwordx4 v[170:171], off
	v_lshl_add_u64 v[170:171], s[78:79], 0, v[130:131]
	s_add_i32 m0, s80, 0x2000
	s_nop 0
	global_load_lds_dwordx4 v[170:171], off
	v_lshl_add_u64 v[170:171], s[64:65], 0, v[132:133]
	s_mov_b32 m0, s22
	s_nop 0
	global_load_lds_dwordx4 v[170:171], off
	s_mov_b32 m0, s23
	s_nop 0
	global_load_lds_dwordx4 v[172:173], off
	s_waitcnt vmcnt(8)
	s_waitcnt lgkmcnt(0)
	s_barrier
	s_setprio 1
	s_waitcnt lgkmcnt(0)
	v_mfma_f32_16x16x32_bf16 v[62:65], v[146:149], v[188:191], v[62:65]
	v_mfma_f32_16x16x32_bf16 v[58:61], v[154:157], v[188:191], v[58:61]
	v_mfma_f32_16x16x32_bf16 v[50:53], v[146:149], v[196:199], v[50:53]
	v_mfma_f32_16x16x32_bf16 v[42:45], v[154:157], v[196:199], v[42:45]
	v_mfma_f32_16x16x32_bf16 v[34:37], v[146:149], v[204:207], v[34:37]
	v_mfma_f32_16x16x32_bf16 v[26:29], v[154:157], v[204:207], v[26:29]
	v_mfma_f32_16x16x32_bf16 v[18:21], v[146:149], v[224:227], v[18:21]
	v_mfma_f32_16x16x32_bf16 v[10:13], v[154:157], v[224:227], v[10:13]
	v_mfma_f32_16x16x32_bf16 v[62:65], v[150:153], v[192:195], v[62:65]
	v_mfma_f32_16x16x32_bf16 v[58:61], v[158:161], v[192:195], v[58:61]
	v_mfma_f32_16x16x32_bf16 v[50:53], v[150:153], v[200:203], v[50:53]
	v_mfma_f32_16x16x32_bf16 v[42:45], v[158:161], v[200:203], v[42:45]
	v_mfma_f32_16x16x32_bf16 v[34:37], v[150:153], v[208:211], v[34:37]
	v_mfma_f32_16x16x32_bf16 v[26:29], v[158:161], v[208:211], v[26:29]
	v_mfma_f32_16x16x32_bf16 v[18:21], v[150:153], v[228:231], v[18:21]
	v_mfma_f32_16x16x32_bf16 v[10:13], v[158:161], v[228:231], v[10:13]
	v_mfma_f32_16x16x32_bf16 v[54:57], v[162:165], v[188:191], v[54:57]
	v_mfma_f32_16x16x32_bf16 v[46:49], v[180:183], v[188:191], v[46:49]
	v_mfma_f32_16x16x32_bf16 v[38:41], v[162:165], v[196:199], v[38:41]
	v_mfma_f32_16x16x32_bf16 v[30:33], v[180:183], v[196:199], v[30:33]
	v_mfma_f32_16x16x32_bf16 v[22:25], v[162:165], v[204:207], v[22:25]
	v_mfma_f32_16x16x32_bf16 v[14:17], v[180:183], v[204:207], v[14:17]
	v_mfma_f32_16x16x32_bf16 v[6:9], v[162:165], v[224:227], v[6:9]
	v_mfma_f32_16x16x32_bf16 v[2:5], v[180:183], v[224:227], v[2:5]
	v_mfma_f32_16x16x32_bf16 v[54:57], v[176:179], v[192:195], v[54:57]
	v_mfma_f32_16x16x32_bf16 v[46:49], v[184:187], v[192:195], v[46:49]
	v_mfma_f32_16x16x32_bf16 v[38:41], v[176:179], v[200:203], v[38:41]
	v_mfma_f32_16x16x32_bf16 v[30:33], v[184:187], v[200:203], v[30:33]
	v_mfma_f32_16x16x32_bf16 v[22:25], v[176:179], v[208:211], v[22:25]
	v_mfma_f32_16x16x32_bf16 v[14:17], v[184:187], v[208:211], v[14:17]
	v_mfma_f32_16x16x32_bf16 v[6:9], v[176:179], v[228:231], v[6:9]
	v_mfma_f32_16x16x32_bf16 v[2:5], v[184:187], v[228:231], v[2:5]
	s_setprio 0
	s_barrier
	s_add_i32 s78, 0, 0x18000
	v_add_u32_e32 v0, s78, v143
	s_add_i32 s79, 0, 0x1c000
	ds_read_b128 v[146:149], v0
	ds_read_b128 v[150:153], v0 offset:1024
	ds_read_b128 v[154:157], v0 offset:2048
	ds_read_b128 v[158:161], v0 offset:3072
	v_add_u32_e32 v0, s79, v143
	ds_read_b128 v[162:165], v0
	ds_read_b128 v[176:179], v0 offset:1024
	ds_read_b128 v[180:183], v0 offset:2048
	ds_read_b128 v[184:187], v0 offset:3072
	s_add_u32 s64, s64, 0x80000
	s_addc_u32 s65, s65, 0
	s_mov_b32 m0, s66
	v_lshl_add_u64 v[212:213], s[64:65], 0, v[132:133]
	ds_read_b128 v[188:191], v144 offset:32768
	ds_read_b128 v[192:195], v144 offset:33792
	ds_read_b128 v[196:199], v144 offset:34816
	ds_read_b128 v[200:203], v144 offset:35840
	ds_read_b128 v[204:207], v144 offset:36864
	ds_read_b128 v[208:211], v144 offset:37888
	ds_read_b128 v[224:227], v144 offset:38912
	ds_read_b128 v[228:231], v144 offset:39936
	global_load_lds_dwordx4 v[212:213], off
	v_lshl_add_u64 v[212:213], s[64:65], 0, v[130:131]
	s_mov_b32 m0, s67
	s_nop 0
	global_load_lds_dwordx4 v[212:213], off
	s_waitcnt vmcnt(8)
	s_waitcnt lgkmcnt(0)
	s_barrier
	s_setprio 1
	s_waitcnt lgkmcnt(0)
	v_mfma_f32_16x16x32_bf16 v[126:129], v[146:149], v[188:191], v[126:129]
	v_mfma_f32_16x16x32_bf16 v[122:125], v[154:157], v[188:191], v[122:125]
	v_mfma_f32_16x16x32_bf16 v[114:117], v[146:149], v[196:199], v[114:117]
	v_mfma_f32_16x16x32_bf16 v[106:109], v[154:157], v[196:199], v[106:109]
	v_mfma_f32_16x16x32_bf16 v[98:101], v[146:149], v[204:207], v[98:101]
	v_mfma_f32_16x16x32_bf16 v[90:93], v[154:157], v[204:207], v[90:93]
	v_mfma_f32_16x16x32_bf16 v[82:85], v[146:149], v[224:227], v[82:85]
	v_mfma_f32_16x16x32_bf16 v[74:77], v[154:157], v[224:227], v[74:77]
	v_mfma_f32_16x16x32_bf16 v[126:129], v[150:153], v[192:195], v[126:129]
	v_mfma_f32_16x16x32_bf16 v[122:125], v[158:161], v[192:195], v[122:125]
	v_mfma_f32_16x16x32_bf16 v[114:117], v[150:153], v[200:203], v[114:117]
	v_mfma_f32_16x16x32_bf16 v[106:109], v[158:161], v[200:203], v[106:109]
	v_mfma_f32_16x16x32_bf16 v[98:101], v[150:153], v[208:211], v[98:101]
	v_mfma_f32_16x16x32_bf16 v[90:93], v[158:161], v[208:211], v[90:93]
	v_mfma_f32_16x16x32_bf16 v[82:85], v[150:153], v[228:231], v[82:85]
	v_mfma_f32_16x16x32_bf16 v[74:77], v[158:161], v[228:231], v[74:77]
	v_mfma_f32_16x16x32_bf16 v[118:121], v[162:165], v[188:191], v[118:121]
	v_mfma_f32_16x16x32_bf16 v[110:113], v[180:183], v[188:191], v[110:113]
	v_mfma_f32_16x16x32_bf16 v[102:105], v[162:165], v[196:199], v[102:105]
	v_mfma_f32_16x16x32_bf16 v[94:97], v[180:183], v[196:199], v[94:97]
	v_mfma_f32_16x16x32_bf16 v[86:89], v[162:165], v[204:207], v[86:89]
	v_mfma_f32_16x16x32_bf16 v[78:81], v[180:183], v[204:207], v[78:81]
	v_mfma_f32_16x16x32_bf16 v[70:73], v[162:165], v[224:227], v[70:73]
	v_mfma_f32_16x16x32_bf16 v[66:69], v[180:183], v[224:227], v[66:69]
	v_mfma_f32_16x16x32_bf16 v[118:121], v[176:179], v[192:195], v[118:121]
	v_mfma_f32_16x16x32_bf16 v[110:113], v[184:187], v[192:195], v[110:113]
	v_mfma_f32_16x16x32_bf16 v[102:105], v[176:179], v[200:203], v[102:105]
	v_mfma_f32_16x16x32_bf16 v[94:97], v[184:187], v[200:203], v[94:97]
	v_mfma_f32_16x16x32_bf16 v[86:89], v[176:179], v[208:211], v[86:89]
	v_mfma_f32_16x16x32_bf16 v[78:81], v[184:187], v[208:211], v[78:81]
	v_mfma_f32_16x16x32_bf16 v[70:73], v[176:179], v[228:231], v[70:73]
	v_mfma_f32_16x16x32_bf16 v[66:69], v[184:187], v[228:231], v[66:69]
	s_setprio 0
	s_barrier
	s_add_i32 s64, s78, s14
	v_lshl_add_u64 v[140:141], v[140:141], 0, s[54:55]
	s_mov_b32 m0, s64
	ds_read_b128 v[188:191], v144 offset:49152
	ds_read_b128 v[192:195], v144 offset:50176
	ds_read_b128 v[196:199], v144 offset:51200
	ds_read_b128 v[200:203], v144 offset:52224
	ds_read_b128 v[204:207], v144 offset:53248
	ds_read_b128 v[208:211], v144 offset:54272
	ds_read_b128 v[224:227], v144 offset:55296
	ds_read_b128 v[228:231], v144 offset:56320
	global_load_lds_dwordx4 v[140:141], off
	s_add_i32 m0, s64, 0x2000
	s_add_u32 s62, s62, 0x80080
	v_lshl_add_u64 v[140:141], v[168:169], 0, s[54:55]
	s_addc_u32 s63, s63, 0
	s_add_i32 s64, s79, s14
	global_load_lds_dwordx4 v[140:141], off
	v_lshl_add_u64 v[140:141], s[62:63], 0, v[132:133]
	s_mov_b32 m0, s64
	s_nop 0
	global_load_lds_dwordx4 v[140:141], off
	v_lshl_add_u64 v[140:141], s[62:63], 0, v[130:131]
	s_add_i32 m0, s64, 0x2000
	s_nop 0
	global_load_lds_dwordx4 v[140:141], off
	v_lshl_add_u64 v[140:141], v[170:171], 0, s[54:55]
	s_mov_b32 m0, s69
	s_nop 0
	global_load_lds_dwordx4 v[140:141], off
	v_lshl_add_u64 v[140:141], v[172:173], 0, s[54:55]
	s_mov_b32 m0, s70
	s_nop 0
	global_load_lds_dwordx4 v[140:141], off
	s_waitcnt vmcnt(8)
	s_waitcnt lgkmcnt(0)
	s_barrier
	s_setprio 1
	s_waitcnt lgkmcnt(0)
	v_mfma_f32_16x16x32_bf16 v[62:65], v[146:149], v[188:191], v[62:65]
	v_mfma_f32_16x16x32_bf16 v[58:61], v[154:157], v[188:191], v[58:61]
	v_mfma_f32_16x16x32_bf16 v[50:53], v[146:149], v[196:199], v[50:53]
	v_mfma_f32_16x16x32_bf16 v[42:45], v[154:157], v[196:199], v[42:45]
	v_mfma_f32_16x16x32_bf16 v[34:37], v[146:149], v[204:207], v[34:37]
	v_mfma_f32_16x16x32_bf16 v[26:29], v[154:157], v[204:207], v[26:29]
	v_mfma_f32_16x16x32_bf16 v[18:21], v[146:149], v[224:227], v[18:21]
	v_mfma_f32_16x16x32_bf16 v[10:13], v[154:157], v[224:227], v[10:13]
	v_mfma_f32_16x16x32_bf16 v[62:65], v[150:153], v[192:195], v[62:65]
	v_mfma_f32_16x16x32_bf16 v[58:61], v[158:161], v[192:195], v[58:61]
	v_mfma_f32_16x16x32_bf16 v[50:53], v[150:153], v[200:203], v[50:53]
	v_mfma_f32_16x16x32_bf16 v[42:45], v[158:161], v[200:203], v[42:45]
	v_mfma_f32_16x16x32_bf16 v[34:37], v[150:153], v[208:211], v[34:37]
	v_mfma_f32_16x16x32_bf16 v[26:29], v[158:161], v[208:211], v[26:29]
	v_mfma_f32_16x16x32_bf16 v[18:21], v[150:153], v[228:231], v[18:21]
	v_mfma_f32_16x16x32_bf16 v[10:13], v[158:161], v[228:231], v[10:13]
	v_mfma_f32_16x16x32_bf16 v[54:57], v[162:165], v[188:191], v[54:57]
	v_mfma_f32_16x16x32_bf16 v[46:49], v[180:183], v[188:191], v[46:49]
	v_mfma_f32_16x16x32_bf16 v[38:41], v[162:165], v[196:199], v[38:41]
	v_mfma_f32_16x16x32_bf16 v[30:33], v[180:183], v[196:199], v[30:33]
	v_mfma_f32_16x16x32_bf16 v[22:25], v[162:165], v[204:207], v[22:25]
	v_mfma_f32_16x16x32_bf16 v[14:17], v[180:183], v[204:207], v[14:17]
	v_mfma_f32_16x16x32_bf16 v[6:9], v[162:165], v[224:227], v[6:9]
	v_mfma_f32_16x16x32_bf16 v[2:5], v[180:183], v[224:227], v[2:5]
	v_mfma_f32_16x16x32_bf16 v[54:57], v[176:179], v[192:195], v[54:57]
	v_mfma_f32_16x16x32_bf16 v[46:49], v[184:187], v[192:195], v[46:49]
	v_mfma_f32_16x16x32_bf16 v[38:41], v[176:179], v[200:203], v[38:41]
	v_mfma_f32_16x16x32_bf16 v[30:33], v[184:187], v[200:203], v[30:33]
	v_mfma_f32_16x16x32_bf16 v[22:25], v[176:179], v[208:211], v[22:25]
	v_mfma_f32_16x16x32_bf16 v[14:17], v[184:187], v[208:211], v[14:17]
	v_mfma_f32_16x16x32_bf16 v[6:9], v[176:179], v[228:231], v[6:9]
	v_mfma_f32_16x16x32_bf16 v[2:5], v[184:187], v[228:231], v[2:5]
	s_setprio 0
	s_barrier
	s_add_i32 s77, s77, 2
	s_add_u32 s73, s73, 0x100
	s_addc_u32 s76, s76, 0
	s_add_u32 s60, s60, 0x100
	s_addc_u32 s61, s61, 0
	s_cmp_gt_u32 s77, 29
	s_cbranch_scc0 .LBB0_251
	s_and_b64 vcc, exec, s[42:43]
	s_cbranch_vccz .LBB0_254
	s_barrier

.LBB0_325:
	s_add_u32 s60, s52, 0xfffe0080
	s_addc_u32 s61, s53, -1
	s_add_i32 s78, 0, 0x10000
	s_cmp_eq_u32 s77, 4
	s_cselect_b32 s63, s43, s61
	s_cselect_b32 s62, s47, s60
	v_add_u32_e32 v143, s78, v139
	s_cselect_b32 s61, s45, s76
	s_cselect_b32 s60, s72, s73
	s_add_i32 s80, 0, 0x14000
	ds_read_b128 v[158:161], v143
	ds_read_b128 v[162:165], v143 offset:1024
	ds_read_b128 v[176:179], v143 offset:2048
	ds_read_b128 v[180:183], v143 offset:3072
	v_add_u32_e32 v143, s80, v139
	ds_read_b128 v[184:187], v143
	ds_read_b128 v[188:191], v143 offset:1024
	ds_read_b128 v[192:195], v143 offset:2048
	ds_read_b128 v[196:199], v143 offset:3072
	v_lshl_add_u64 v[168:169], s[52:53], 0, v[156:157]
	s_add_i32 m0, s26, 0xc000
	ds_read_b128 v[200:203], v141
	ds_read_b128 v[204:207], v141 offset:1024
	ds_read_b128 v[208:211], v141 offset:2048
	ds_read_b128 v[224:227], v141 offset:3072
	ds_read_b128 v[228:231], v141 offset:4096
	ds_read_b128 v[232:235], v141 offset:5120
	ds_read_b128 v[236:239], v141 offset:6144
	ds_read_b128 v[244:247], v141 offset:7168
	global_load_lds_dwordx4 v[168:169], off
	v_lshl_add_u64 v[168:169], s[52:53], 0, v[154:155]
	s_add_i32 m0, s26, 0xe000
	s_nop 0
	global_load_lds_dwordx4 v[168:169], off
	s_waitcnt vmcnt(8)
	s_waitcnt lgkmcnt(0)
	s_barrier
	s_setprio 1
	s_waitcnt lgkmcnt(0)
	v_mfma_f32_16x16x32_bf16 v[126:129], v[158:161], v[200:203], v[126:129]
	v_mfma_f32_16x16x32_bf16 v[122:125], v[176:179], v[200:203], v[122:125]
	v_mfma_f32_16x16x32_bf16 v[118:121], v[158:161], v[208:211], v[118:121]
	v_mfma_f32_16x16x32_bf16 v[110:113], v[176:179], v[208:211], v[110:113]
	v_mfma_f32_16x16x32_bf16 v[102:105], v[158:161], v[228:231], v[102:105]
	v_mfma_f32_16x16x32_bf16 v[94:97], v[176:179], v[228:231], v[94:97]
	v_mfma_f32_16x16x32_bf16 v[86:89], v[158:161], v[236:239], v[86:89]
	v_mfma_f32_16x16x32_bf16 v[78:81], v[176:179], v[236:239], v[78:81]
	v_mfma_f32_16x16x32_bf16 v[126:129], v[162:165], v[204:207], v[126:129]
	v_mfma_f32_16x16x32_bf16 v[122:125], v[180:183], v[204:207], v[122:125]
	v_mfma_f32_16x16x32_bf16 v[118:121], v[162:165], v[224:227], v[118:121]
	v_mfma_f32_16x16x32_bf16 v[110:113], v[180:183], v[224:227], v[110:113]
	v_mfma_f32_16x16x32_bf16 v[102:105], v[162:165], v[232:235], v[102:105]
	v_mfma_f32_16x16x32_bf16 v[94:97], v[180:183], v[232:235], v[94:97]
	v_mfma_f32_16x16x32_bf16 v[86:89], v[162:165], v[244:247], v[86:89]
	v_mfma_f32_16x16x32_bf16 v[78:81], v[180:183], v[244:247], v[78:81]
	v_mfma_f32_16x16x32_bf16 v[114:117], v[184:187], v[200:203], v[114:117]
	v_mfma_f32_16x16x32_bf16 v[106:109], v[192:195], v[200:203], v[106:109]
	v_mfma_f32_16x16x32_bf16 v[98:101], v[184:187], v[208:211], v[98:101]
	v_mfma_f32_16x16x32_bf16 v[90:93], v[192:195], v[208:211], v[90:93]
	v_mfma_f32_16x16x32_bf16 v[82:85], v[184:187], v[228:231], v[82:85]
	v_mfma_f32_16x16x32_bf16 v[74:77], v[192:195], v[228:231], v[74:77]
	v_mfma_f32_16x16x32_bf16 v[70:73], v[184:187], v[236:239], v[70:73]
	v_mfma_f32_16x16x32_bf16 v[66:69], v[192:195], v[236:239], v[66:69]
	v_mfma_f32_16x16x32_bf16 v[114:117], v[188:191], v[204:207], v[114:117]
	v_mfma_f32_16x16x32_bf16 v[106:109], v[196:199], v[204:207], v[106:109]
	v_mfma_f32_16x16x32_bf16 v[98:101], v[188:191], v[224:227], v[98:101]
	v_mfma_f32_16x16x32_bf16 v[90:93], v[196:199], v[224:227], v[90:93]
	v_mfma_f32_16x16x32_bf16 v[82:85], v[188:191], v[232:235], v[82:85]
	v_mfma_f32_16x16x32_bf16 v[74:77], v[196:199], v[232:235], v[74:77]
	v_mfma_f32_16x16x32_bf16 v[70:73], v[188:191], v[244:247], v[70:73]
	v_mfma_f32_16x16x32_bf16 v[66:69], v[196:199], v[244:247], v[66:69]
	s_setprio 0
	s_barrier
	s_add_i32 s78, s78, s23
	v_lshl_add_u64 v[168:169], s[60:61], 0, v[132:133]
	s_mov_b32 m0, s78
	ds_read_b128 v[200:203], v141 offset:16384
	ds_read_b128 v[204:207], v141 offset:17408
	ds_read_b128 v[208:211], v141 offset:18432
	ds_read_b128 v[224:227], v141 offset:19456
	ds_read_b128 v[228:231], v141 offset:20480
	ds_read_b128 v[232:235], v141 offset:21504
	ds_read_b128 v[236:239], v141 offset:22528
	ds_read_b128 v[244:247], v141 offset:23552
	global_load_lds_dwordx4 v[168:169], off
	s_add_i32 m0, s78, 0x2000
	s_add_u32 s78, s60, 0x20000
	v_lshl_add_u64 v[212:213], s[60:61], 0, v[136:137]
	s_addc_u32 s79, s61, 0
	s_add_i32 s80, s80, s23
	global_load_lds_dwordx4 v[212:213], off
	v_lshl_add_u64 v[248:249], s[78:79], 0, v[132:133]
	s_mov_b32 m0, s80
	v_lshl_add_u64 v[170:171], s[62:63], 0, v[134:135]
	global_load_lds_dwordx4 v[248:249], off
	v_lshl_add_u64 v[248:249], s[78:79], 0, v[136:137]
	s_add_i32 m0, s80, 0x2000
	s_nop 0
	global_load_lds_dwordx4 v[248:249], off
	v_lshl_add_u64 v[248:249], s[62:63], 0, v[130:131]
	s_mov_b32 m0, s26
	s_nop 0
	global_load_lds_dwordx4 v[248:249], off
	s_mov_b32 m0, s41
	s_nop 0
	global_load_lds_dwordx4 v[170:171], off
	s_waitcnt vmcnt(8)
	s_waitcnt lgkmcnt(0)
	s_barrier
	s_setprio 1
	s_waitcnt lgkmcnt(0)
	v_mfma_f32_16x16x32_bf16 v[62:65], v[158:161], v[200:203], v[62:65]
	v_mfma_f32_16x16x32_bf16 v[58:61], v[176:179], v[200:203], v[58:61]
	v_mfma_f32_16x16x32_bf16 v[54:57], v[158:161], v[208:211], v[54:57]
	v_mfma_f32_16x16x32_bf16 v[46:49], v[176:179], v[208:211], v[46:49]
	v_mfma_f32_16x16x32_bf16 v[38:41], v[158:161], v[228:231], v[38:41]
	v_mfma_f32_16x16x32_bf16 v[30:33], v[176:179], v[228:231], v[30:33]
	v_mfma_f32_16x16x32_bf16 v[22:25], v[158:161], v[236:239], v[22:25]
	v_mfma_f32_16x16x32_bf16 v[14:17], v[176:179], v[236:239], v[14:17]
	v_mfma_f32_16x16x32_bf16 v[62:65], v[162:165], v[204:207], v[62:65]
	v_mfma_f32_16x16x32_bf16 v[58:61], v[180:183], v[204:207], v[58:61]
	v_mfma_f32_16x16x32_bf16 v[54:57], v[162:165], v[224:227], v[54:57]
	v_mfma_f32_16x16x32_bf16 v[46:49], v[180:183], v[224:227], v[46:49]
	v_mfma_f32_16x16x32_bf16 v[38:41], v[162:165], v[232:235], v[38:41]
	v_mfma_f32_16x16x32_bf16 v[30:33], v[180:183], v[232:235], v[30:33]
	v_mfma_f32_16x16x32_bf16 v[22:25], v[162:165], v[244:247], v[22:25]
	v_mfma_f32_16x16x32_bf16 v[14:17], v[180:183], v[244:247], v[14:17]
	v_mfma_f32_16x16x32_bf16 v[50:53], v[184:187], v[200:203], v[50:53]
	v_mfma_f32_16x16x32_bf16 v[42:45], v[192:195], v[200:203], v[42:45]
	v_mfma_f32_16x16x32_bf16 v[34:37], v[184:187], v[208:211], v[34:37]
	v_mfma_f32_16x16x32_bf16 v[26:29], v[192:195], v[208:211], v[26:29]
	v_mfma_f32_16x16x32_bf16 v[18:21], v[184:187], v[228:231], v[18:21]
	v_mfma_f32_16x16x32_bf16 v[10:13], v[192:195], v[228:231], v[10:13]
	v_mfma_f32_16x16x32_bf16 v[6:9], v[184:187], v[236:239], v[6:9]
	v_mfma_f32_16x16x32_bf16 v[2:5], v[192:195], v[236:239], v[2:5]
	v_mfma_f32_16x16x32_bf16 v[50:53], v[188:191], v[204:207], v[50:53]
	v_mfma_f32_16x16x32_bf16 v[42:45], v[196:199], v[204:207], v[42:45]
	v_mfma_f32_16x16x32_bf16 v[34:37], v[188:191], v[224:227], v[34:37]
	v_mfma_f32_16x16x32_bf16 v[26:29], v[196:199], v[224:227], v[26:29]
	v_mfma_f32_16x16x32_bf16 v[18:21], v[188:191], v[232:235], v[18:21]
	v_mfma_f32_16x16x32_bf16 v[10:13], v[196:199], v[232:235], v[10:13]
	v_mfma_f32_16x16x32_bf16 v[6:9], v[188:191], v[244:247], v[6:9]
	v_mfma_f32_16x16x32_bf16 v[2:5], v[196:199], v[244:247], v[2:5]
	s_setprio 0
	s_barrier
	s_add_i32 s78, 0, 0x18000
	v_add_u32_e32 v143, s78, v139
	s_add_i32 s79, 0, 0x1c000
	ds_read_b128 v[158:161], v143
	ds_read_b128 v[162:165], v143 offset:1024
	ds_read_b128 v[176:179], v143 offset:2048
	ds_read_b128 v[180:183], v143 offset:3072
	v_add_u32_e32 v143, s79, v139
	ds_read_b128 v[184:187], v143
	ds_read_b128 v[188:191], v143 offset:1024
	ds_read_b128 v[192:195], v143 offset:2048
	ds_read_b128 v[196:199], v143 offset:3072
	s_add_u32 s62, s62, 0x20000
	s_addc_u32 s63, s63, 0
	s_mov_b32 m0, s64
	v_lshl_add_u64 v[172:173], s[62:63], 0, v[130:131]
	ds_read_b128 v[200:203], v141 offset:32768
	ds_read_b128 v[204:207], v141 offset:33792
	ds_read_b128 v[208:211], v141 offset:34816
	ds_read_b128 v[224:227], v141 offset:35840
	ds_read_b128 v[228:231], v141 offset:36864
	ds_read_b128 v[232:235], v141 offset:37888
	ds_read_b128 v[236:239], v141 offset:38912
	ds_read_b128 v[244:247], v141 offset:39936
	global_load_lds_dwordx4 v[172:173], off
	v_lshl_add_u64 v[172:173], s[62:63], 0, v[134:135]
	s_mov_b32 m0, s65
	s_nop 0
	global_load_lds_dwordx4 v[172:173], off
	s_waitcnt vmcnt(8)
	s_waitcnt lgkmcnt(0)
	s_barrier
	s_setprio 1
	s_waitcnt lgkmcnt(0)
	v_mfma_f32_16x16x32_bf16 v[126:129], v[158:161], v[200:203], v[126:129]
	v_mfma_f32_16x16x32_bf16 v[122:125], v[176:179], v[200:203], v[122:125]
	v_mfma_f32_16x16x32_bf16 v[118:121], v[158:161], v[208:211], v[118:121]
	v_mfma_f32_16x16x32_bf16 v[110:113], v[176:179], v[208:211], v[110:113]
	v_mfma_f32_16x16x32_bf16 v[102:105], v[158:161], v[228:231], v[102:105]
	v_mfma_f32_16x16x32_bf16 v[94:97], v[176:179], v[228:231], v[94:97]
	v_mfma_f32_16x16x32_bf16 v[86:89], v[158:161], v[236:239], v[86:89]
	v_mfma_f32_16x16x32_bf16 v[78:81], v[176:179], v[236:239], v[78:81]
	v_mfma_f32_16x16x32_bf16 v[126:129], v[162:165], v[204:207], v[126:129]
	v_mfma_f32_16x16x32_bf16 v[122:125], v[180:183], v[204:207], v[122:125]
	v_mfma_f32_16x16x32_bf16 v[118:121], v[162:165], v[224:227], v[118:121]
	v_mfma_f32_16x16x32_bf16 v[110:113], v[180:183], v[224:227], v[110:113]
	v_mfma_f32_16x16x32_bf16 v[102:105], v[162:165], v[232:235], v[102:105]
	v_mfma_f32_16x16x32_bf16 v[94:97], v[180:183], v[232:235], v[94:97]
	v_mfma_f32_16x16x32_bf16 v[86:89], v[162:165], v[244:247], v[86:89]
	v_mfma_f32_16x16x32_bf16 v[78:81], v[180:183], v[244:247], v[78:81]
	v_mfma_f32_16x16x32_bf16 v[114:117], v[184:187], v[200:203], v[114:117]
	v_mfma_f32_16x16x32_bf16 v[106:109], v[192:195], v[200:203], v[106:109]
	v_mfma_f32_16x16x32_bf16 v[98:101], v[184:187], v[208:211], v[98:101]
	v_mfma_f32_16x16x32_bf16 v[90:93], v[192:195], v[208:211], v[90:93]
	v_mfma_f32_16x16x32_bf16 v[82:85], v[184:187], v[228:231], v[82:85]
	v_mfma_f32_16x16x32_bf16 v[74:77], v[192:195], v[228:231], v[74:77]
	v_mfma_f32_16x16x32_bf16 v[70:73], v[184:187], v[236:239], v[70:73]
	v_mfma_f32_16x16x32_bf16 v[66:69], v[192:195], v[236:239], v[66:69]
	v_mfma_f32_16x16x32_bf16 v[114:117], v[188:191], v[204:207], v[114:117]
	v_mfma_f32_16x16x32_bf16 v[106:109], v[196:199], v[204:207], v[106:109]
	v_mfma_f32_16x16x32_bf16 v[98:101], v[188:191], v[224:227], v[98:101]
	v_mfma_f32_16x16x32_bf16 v[90:93], v[196:199], v[224:227], v[90:93]
	v_mfma_f32_16x16x32_bf16 v[82:85], v[188:191], v[232:235], v[82:85]
	v_mfma_f32_16x16x32_bf16 v[74:77], v[196:199], v[232:235], v[74:77]
	v_mfma_f32_16x16x32_bf16 v[70:73], v[188:191], v[244:247], v[70:73]
	v_mfma_f32_16x16x32_bf16 v[66:69], v[196:199], v[244:247], v[66:69]
	s_setprio 0
	s_barrier
	s_add_i32 s62, s78, s23
	v_lshl_add_u64 v[168:169], v[168:169], 0, s[54:55]
	s_mov_b32 m0, s62
	ds_read_b128 v[200:203], v141 offset:49152
	ds_read_b128 v[204:207], v141 offset:50176
	ds_read_b128 v[208:211], v141 offset:51200
	ds_read_b128 v[224:227], v141 offset:52224
	ds_read_b128 v[228:231], v141 offset:53248
	ds_read_b128 v[232:235], v141 offset:54272
	ds_read_b128 v[236:239], v141 offset:55296
	ds_read_b128 v[244:247], v141 offset:56320
	global_load_lds_dwordx4 v[168:169], off
	s_add_i32 m0, s62, 0x2000
	s_add_u32 s60, s60, 0x20080
	v_lshl_add_u64 v[168:169], v[212:213], 0, s[54:55]
	s_addc_u32 s61, s61, 0
	s_add_i32 s62, s79, s23
	global_load_lds_dwordx4 v[168:169], off
	v_lshl_add_u64 v[168:169], s[60:61], 0, v[132:133]
	s_mov_b32 m0, s62
	s_nop 0
	global_load_lds_dwordx4 v[168:169], off
	v_lshl_add_u64 v[168:169], s[60:61], 0, v[136:137]
	s_add_i32 m0, s62, 0x2000
	s_nop 0
	global_load_lds_dwordx4 v[168:169], off
	v_lshl_add_u64 v[168:169], v[248:249], 0, s[54:55]
	s_mov_b32 m0, s68
	s_nop 0
	global_load_lds_dwordx4 v[168:169], off
	v_lshl_add_u64 v[168:169], v[170:171], 0, s[54:55]
	s_mov_b32 m0, s69
	s_nop 0
	global_load_lds_dwordx4 v[168:169], off
	s_waitcnt vmcnt(8)
	s_waitcnt lgkmcnt(0)
	s_barrier
	s_setprio 1
	s_waitcnt lgkmcnt(0)
	v_mfma_f32_16x16x32_bf16 v[62:65], v[158:161], v[200:203], v[62:65]
	v_mfma_f32_16x16x32_bf16 v[58:61], v[176:179], v[200:203], v[58:61]
	v_mfma_f32_16x16x32_bf16 v[54:57], v[158:161], v[208:211], v[54:57]
	v_mfma_f32_16x16x32_bf16 v[46:49], v[176:179], v[208:211], v[46:49]
	v_mfma_f32_16x16x32_bf16 v[38:41], v[158:161], v[228:231], v[38:41]
	v_mfma_f32_16x16x32_bf16 v[30:33], v[176:179], v[228:231], v[30:33]
	v_mfma_f32_16x16x32_bf16 v[22:25], v[158:161], v[236:239], v[22:25]
	v_mfma_f32_16x16x32_bf16 v[14:17], v[176:179], v[236:239], v[14:17]
	v_mfma_f32_16x16x32_bf16 v[62:65], v[162:165], v[204:207], v[62:65]
	v_mfma_f32_16x16x32_bf16 v[58:61], v[180:183], v[204:207], v[58:61]
	v_mfma_f32_16x16x32_bf16 v[54:57], v[162:165], v[224:227], v[54:57]
	v_mfma_f32_16x16x32_bf16 v[46:49], v[180:183], v[224:227], v[46:49]
	v_mfma_f32_16x16x32_bf16 v[38:41], v[162:165], v[232:235], v[38:41]
	v_mfma_f32_16x16x32_bf16 v[30:33], v[180:183], v[232:235], v[30:33]
	v_mfma_f32_16x16x32_bf16 v[22:25], v[162:165], v[244:247], v[22:25]
	v_mfma_f32_16x16x32_bf16 v[14:17], v[180:183], v[244:247], v[14:17]
	v_mfma_f32_16x16x32_bf16 v[50:53], v[184:187], v[200:203], v[50:53]
	v_mfma_f32_16x16x32_bf16 v[42:45], v[192:195], v[200:203], v[42:45]
	v_mfma_f32_16x16x32_bf16 v[34:37], v[184:187], v[208:211], v[34:37]
	v_mfma_f32_16x16x32_bf16 v[26:29], v[192:195], v[208:211], v[26:29]
	v_mfma_f32_16x16x32_bf16 v[18:21], v[184:187], v[228:231], v[18:21]
	v_mfma_f32_16x16x32_bf16 v[10:13], v[192:195], v[228:231], v[10:13]
	v_mfma_f32_16x16x32_bf16 v[6:9], v[184:187], v[236:239], v[6:9]
	v_mfma_f32_16x16x32_bf16 v[2:5], v[192:195], v[236:239], v[2:5]
	v_mfma_f32_16x16x32_bf16 v[50:53], v[188:191], v[204:207], v[50:53]
	v_mfma_f32_16x16x32_bf16 v[42:45], v[196:199], v[204:207], v[42:45]
	v_mfma_f32_16x16x32_bf16 v[34:37], v[188:191], v[224:227], v[34:37]
	v_mfma_f32_16x16x32_bf16 v[26:29], v[196:199], v[224:227], v[26:29]
	v_mfma_f32_16x16x32_bf16 v[18:21], v[188:191], v[232:235], v[18:21]
	v_mfma_f32_16x16x32_bf16 v[10:13], v[196:199], v[232:235], v[10:13]
	v_mfma_f32_16x16x32_bf16 v[6:9], v[188:191], v[244:247], v[6:9]
	v_mfma_f32_16x16x32_bf16 v[2:5], v[196:199], v[244:247], v[2:5]
	s_setprio 0
	s_barrier
	s_add_i32 s77, s77, 2
	s_add_u32 s73, s73, 0x100
	s_addc_u32 s76, s76, 0
	s_add_u32 s52, s52, 0x100
	s_addc_u32 s53, s53, 0
	s_cmp_gt_u32 s77, 5
	s_cbranch_scc0 .LBB0_325
	s_and_b64 vcc, exec, s[24:25]
	s_cbranch_vccz .LBB0_328
	s_barrier

.LBB0_387:
	s_add_u32 s60, s52, 0xfff80080
	s_addc_u32 s61, s53, -1
	s_add_i32 s77, 0, 0x10000
	s_cmp_eq_u32 s76, 28
	s_cselect_b32 s63, s47, s61
	s_cselect_b32 s62, s70, s60
	v_add_u32_e32 v141, s77, v139
	s_cselect_b32 s61, s45, s73
	s_cselect_b32 s60, s71, s72
	s_add_i32 s80, 0, 0x14000
	ds_read_b128 v[142:145], v141
	ds_read_b128 v[146:149], v141 offset:1024
	ds_read_b128 v[150:153], v141 offset:2048
	ds_read_b128 v[154:157], v141 offset:3072
	v_add_u32_e32 v141, s80, v139
	ds_read_b128 v[158:161], v141
	ds_read_b128 v[162:165], v141 offset:1024
	ds_read_b128 v[176:179], v141 offset:2048
	ds_read_b128 v[180:183], v141 offset:3072
	v_lshl_add_u64 v[168:169], s[52:53], 0, v[136:137]
	s_add_i32 m0, s23, 0xc000
	ds_read_b128 v[184:187], v140
	ds_read_b128 v[188:191], v140 offset:1024
	ds_read_b128 v[192:195], v140 offset:2048
	ds_read_b128 v[196:199], v140 offset:3072
	ds_read_b128 v[200:203], v140 offset:4096
	ds_read_b128 v[204:207], v140 offset:5120
	ds_read_b128 v[208:211], v140 offset:6144
	ds_read_b128 v[224:227], v140 offset:7168
	global_load_lds_dwordx4 v[168:169], off
	v_lshl_add_u64 v[168:169], s[52:53], 0, v[134:135]
	s_add_i32 m0, s23, 0xe000
	s_nop 0
	global_load_lds_dwordx4 v[168:169], off
	s_waitcnt vmcnt(8)
	s_waitcnt lgkmcnt(0)
	s_barrier
	s_setprio 1
	s_waitcnt lgkmcnt(0)
	v_mfma_f32_16x16x32_bf16 v[126:129], v[142:145], v[184:187], v[126:129]
	v_mfma_f32_16x16x32_bf16 v[122:125], v[150:153], v[184:187], v[122:125]
	v_mfma_f32_16x16x32_bf16 v[118:121], v[142:145], v[192:195], v[118:121]
	v_mfma_f32_16x16x32_bf16 v[114:117], v[150:153], v[192:195], v[114:117]
	v_mfma_f32_16x16x32_bf16 v[110:113], v[142:145], v[200:203], v[110:113]
	v_mfma_f32_16x16x32_bf16 v[102:105], v[150:153], v[200:203], v[102:105]
	v_mfma_f32_16x16x32_bf16 v[94:97], v[142:145], v[208:211], v[94:97]
	v_mfma_f32_16x16x32_bf16 v[86:89], v[150:153], v[208:211], v[86:89]
	v_mfma_f32_16x16x32_bf16 v[126:129], v[146:149], v[188:191], v[126:129]
	v_mfma_f32_16x16x32_bf16 v[122:125], v[154:157], v[188:191], v[122:125]
	v_mfma_f32_16x16x32_bf16 v[118:121], v[146:149], v[196:199], v[118:121]
	v_mfma_f32_16x16x32_bf16 v[114:117], v[154:157], v[196:199], v[114:117]
	v_mfma_f32_16x16x32_bf16 v[110:113], v[146:149], v[204:207], v[110:113]
	v_mfma_f32_16x16x32_bf16 v[102:105], v[154:157], v[204:207], v[102:105]
	v_mfma_f32_16x16x32_bf16 v[94:97], v[146:149], v[224:227], v[94:97]
	v_mfma_f32_16x16x32_bf16 v[86:89], v[154:157], v[224:227], v[86:89]
	v_mfma_f32_16x16x32_bf16 v[106:109], v[158:161], v[184:187], v[106:109]
	v_mfma_f32_16x16x32_bf16 v[98:101], v[176:179], v[184:187], v[98:101]
	v_mfma_f32_16x16x32_bf16 v[90:93], v[158:161], v[192:195], v[90:93]
	v_mfma_f32_16x16x32_bf16 v[82:85], v[176:179], v[192:195], v[82:85]
	v_mfma_f32_16x16x32_bf16 v[78:81], v[158:161], v[200:203], v[78:81]
	v_mfma_f32_16x16x32_bf16 v[74:77], v[176:179], v[200:203], v[74:77]
	v_mfma_f32_16x16x32_bf16 v[70:73], v[158:161], v[208:211], v[70:73]
	v_mfma_f32_16x16x32_bf16 v[66:69], v[176:179], v[208:211], v[66:69]
	v_mfma_f32_16x16x32_bf16 v[106:109], v[162:165], v[188:191], v[106:109]
	v_mfma_f32_16x16x32_bf16 v[98:101], v[180:183], v[188:191], v[98:101]
	v_mfma_f32_16x16x32_bf16 v[90:93], v[162:165], v[196:199], v[90:93]
	v_mfma_f32_16x16x32_bf16 v[82:85], v[180:183], v[196:199], v[82:85]
	v_mfma_f32_16x16x32_bf16 v[78:81], v[162:165], v[204:207], v[78:81]
	v_mfma_f32_16x16x32_bf16 v[74:77], v[180:183], v[204:207], v[74:77]
	v_mfma_f32_16x16x32_bf16 v[70:73], v[162:165], v[224:227], v[70:73]
	v_mfma_f32_16x16x32_bf16 v[66:69], v[180:183], v[224:227], v[66:69]
	s_setprio 0
	s_barrier
	s_add_i32 s77, s77, s17
	v_lshl_add_u64 v[168:169], s[60:61], 0, v[132:133]
	s_mov_b32 m0, s77
	ds_read_b128 v[184:187], v140 offset:16384
	ds_read_b128 v[188:191], v140 offset:17408
	ds_read_b128 v[192:195], v140 offset:18432
	ds_read_b128 v[196:199], v140 offset:19456
	ds_read_b128 v[200:203], v140 offset:20480
	ds_read_b128 v[204:207], v140 offset:21504
	ds_read_b128 v[208:211], v140 offset:22528
	ds_read_b128 v[224:227], v140 offset:23552
	global_load_lds_dwordx4 v[168:169], off
	s_add_i32 m0, s77, 0x2000
	s_add_u32 s78, s60, 0x80000
	v_lshl_add_u64 v[212:213], s[60:61], 0, v[130:131]
	s_addc_u32 s79, s61, 0
	s_add_i32 s77, s80, s17
	global_load_lds_dwordx4 v[212:213], off
	v_lshl_add_u64 v[228:229], s[78:79], 0, v[132:133]
	s_mov_b32 m0, s77
	v_lshl_add_u64 v[230:231], s[62:63], 0, v[130:131]
	global_load_lds_dwordx4 v[228:229], off
	v_lshl_add_u64 v[228:229], s[78:79], 0, v[130:131]
	s_add_i32 m0, s77, 0x2000
	s_nop 0
	global_load_lds_dwordx4 v[228:229], off
	v_lshl_add_u64 v[228:229], s[62:63], 0, v[132:133]
	s_mov_b32 m0, s23
	s_nop 0
	global_load_lds_dwordx4 v[228:229], off
	s_mov_b32 m0, s41
	s_nop 0
	global_load_lds_dwordx4 v[230:231], off
	s_waitcnt vmcnt(8)
	s_waitcnt lgkmcnt(0)
	s_barrier
	s_setprio 1
	s_waitcnt lgkmcnt(0)
	v_mfma_f32_16x16x32_bf16 v[62:65], v[142:145], v[184:187], v[62:65]
	v_mfma_f32_16x16x32_bf16 v[58:61], v[150:153], v[184:187], v[58:61]
	v_mfma_f32_16x16x32_bf16 v[54:57], v[142:145], v[192:195], v[54:57]
	v_mfma_f32_16x16x32_bf16 v[50:53], v[150:153], v[192:195], v[50:53]
	v_mfma_f32_16x16x32_bf16 v[46:49], v[142:145], v[200:203], v[46:49]
	v_mfma_f32_16x16x32_bf16 v[38:41], v[150:153], v[200:203], v[38:41]
	v_mfma_f32_16x16x32_bf16 v[30:33], v[142:145], v[208:211], v[30:33]
	v_mfma_f32_16x16x32_bf16 v[22:25], v[150:153], v[208:211], v[22:25]
	v_mfma_f32_16x16x32_bf16 v[62:65], v[146:149], v[188:191], v[62:65]
	v_mfma_f32_16x16x32_bf16 v[58:61], v[154:157], v[188:191], v[58:61]
	v_mfma_f32_16x16x32_bf16 v[54:57], v[146:149], v[196:199], v[54:57]
	v_mfma_f32_16x16x32_bf16 v[50:53], v[154:157], v[196:199], v[50:53]
	v_mfma_f32_16x16x32_bf16 v[46:49], v[146:149], v[204:207], v[46:49]
	v_mfma_f32_16x16x32_bf16 v[38:41], v[154:157], v[204:207], v[38:41]
	v_mfma_f32_16x16x32_bf16 v[30:33], v[146:149], v[224:227], v[30:33]
	v_mfma_f32_16x16x32_bf16 v[22:25], v[154:157], v[224:227], v[22:25]
	v_mfma_f32_16x16x32_bf16 v[42:45], v[158:161], v[184:187], v[42:45]
	v_mfma_f32_16x16x32_bf16 v[34:37], v[176:179], v[184:187], v[34:37]
	v_mfma_f32_16x16x32_bf16 v[26:29], v[158:161], v[192:195], v[26:29]
	v_mfma_f32_16x16x32_bf16 v[18:21], v[176:179], v[192:195], v[18:21]
	v_mfma_f32_16x16x32_bf16 v[14:17], v[158:161], v[200:203], v[14:17]
	v_mfma_f32_16x16x32_bf16 v[10:13], v[176:179], v[200:203], v[10:13]
	v_mfma_f32_16x16x32_bf16 v[6:9], v[158:161], v[208:211], v[6:9]
	v_mfma_f32_16x16x32_bf16 v[2:5], v[176:179], v[208:211], v[2:5]
	v_mfma_f32_16x16x32_bf16 v[42:45], v[162:165], v[188:191], v[42:45]
	v_mfma_f32_16x16x32_bf16 v[34:37], v[180:183], v[188:191], v[34:37]
	v_mfma_f32_16x16x32_bf16 v[26:29], v[162:165], v[196:199], v[26:29]
	v_mfma_f32_16x16x32_bf16 v[18:21], v[180:183], v[196:199], v[18:21]
	v_mfma_f32_16x16x32_bf16 v[14:17], v[162:165], v[204:207], v[14:17]
	v_mfma_f32_16x16x32_bf16 v[10:13], v[180:183], v[204:207], v[10:13]
	v_mfma_f32_16x16x32_bf16 v[6:9], v[162:165], v[224:227], v[6:9]
	v_mfma_f32_16x16x32_bf16 v[2:5], v[180:183], v[224:227], v[2:5]
	s_setprio 0
	s_barrier
	s_add_i32 s77, 0, 0x18000
	v_add_u32_e32 v141, s77, v139
	s_add_i32 s78, 0, 0x1c000
	ds_read_b128 v[142:145], v141
	ds_read_b128 v[146:149], v141 offset:1024
	ds_read_b128 v[150:153], v141 offset:2048
	ds_read_b128 v[154:157], v141 offset:3072
	v_add_u32_e32 v141, s78, v139
	ds_read_b128 v[158:161], v141
	ds_read_b128 v[162:165], v141 offset:1024
	ds_read_b128 v[176:179], v141 offset:2048
	ds_read_b128 v[180:183], v141 offset:3072
	s_add_u32 s62, s62, 0x80000
	s_addc_u32 s63, s63, 0
	s_mov_b32 m0, s64
	v_lshl_add_u64 v[232:233], s[62:63], 0, v[132:133]
	ds_read_b128 v[184:187], v140 offset:32768
	ds_read_b128 v[188:191], v140 offset:33792
	ds_read_b128 v[192:195], v140 offset:34816
	ds_read_b128 v[196:199], v140 offset:35840
	ds_read_b128 v[200:203], v140 offset:36864
	ds_read_b128 v[204:207], v140 offset:37888
	ds_read_b128 v[208:211], v140 offset:38912
	ds_read_b128 v[224:227], v140 offset:39936
	global_load_lds_dwordx4 v[232:233], off
	v_lshl_add_u64 v[232:233], s[62:63], 0, v[130:131]
	s_mov_b32 m0, s65
	s_nop 0
	global_load_lds_dwordx4 v[232:233], off
	s_waitcnt vmcnt(8)
	s_waitcnt lgkmcnt(0)
	s_barrier
	s_setprio 1
	s_waitcnt lgkmcnt(0)
	v_mfma_f32_16x16x32_bf16 v[126:129], v[142:145], v[184:187], v[126:129]
	v_mfma_f32_16x16x32_bf16 v[122:125], v[150:153], v[184:187], v[122:125]
	v_mfma_f32_16x16x32_bf16 v[118:121], v[142:145], v[192:195], v[118:121]
	v_mfma_f32_16x16x32_bf16 v[114:117], v[150:153], v[192:195], v[114:117]
	v_mfma_f32_16x16x32_bf16 v[110:113], v[142:145], v[200:203], v[110:113]
	v_mfma_f32_16x16x32_bf16 v[102:105], v[150:153], v[200:203], v[102:105]
	v_mfma_f32_16x16x32_bf16 v[94:97], v[142:145], v[208:211], v[94:97]
	v_mfma_f32_16x16x32_bf16 v[86:89], v[150:153], v[208:211], v[86:89]
	v_mfma_f32_16x16x32_bf16 v[126:129], v[146:149], v[188:191], v[126:129]
	v_mfma_f32_16x16x32_bf16 v[122:125], v[154:157], v[188:191], v[122:125]
	v_mfma_f32_16x16x32_bf16 v[118:121], v[146:149], v[196:199], v[118:121]
	v_mfma_f32_16x16x32_bf16 v[114:117], v[154:157], v[196:199], v[114:117]
	v_mfma_f32_16x16x32_bf16 v[110:113], v[146:149], v[204:207], v[110:113]
	v_mfma_f32_16x16x32_bf16 v[102:105], v[154:157], v[204:207], v[102:105]
	v_mfma_f32_16x16x32_bf16 v[94:97], v[146:149], v[224:227], v[94:97]
	v_mfma_f32_16x16x32_bf16 v[86:89], v[154:157], v[224:227], v[86:89]
	v_mfma_f32_16x16x32_bf16 v[106:109], v[158:161], v[184:187], v[106:109]
	v_mfma_f32_16x16x32_bf16 v[98:101], v[176:179], v[184:187], v[98:101]
	v_mfma_f32_16x16x32_bf16 v[90:93], v[158:161], v[192:195], v[90:93]
	v_mfma_f32_16x16x32_bf16 v[82:85], v[176:179], v[192:195], v[82:85]
	v_mfma_f32_16x16x32_bf16 v[78:81], v[158:161], v[200:203], v[78:81]
	v_mfma_f32_16x16x32_bf16 v[74:77], v[176:179], v[200:203], v[74:77]
	v_mfma_f32_16x16x32_bf16 v[70:73], v[158:161], v[208:211], v[70:73]
	v_mfma_f32_16x16x32_bf16 v[66:69], v[176:179], v[208:211], v[66:69]
	v_mfma_f32_16x16x32_bf16 v[106:109], v[162:165], v[188:191], v[106:109]
	v_mfma_f32_16x16x32_bf16 v[98:101], v[180:183], v[188:191], v[98:101]
	v_mfma_f32_16x16x32_bf16 v[90:93], v[162:165], v[196:199], v[90:93]
	v_mfma_f32_16x16x32_bf16 v[82:85], v[180:183], v[196:199], v[82:85]
	v_mfma_f32_16x16x32_bf16 v[78:81], v[162:165], v[204:207], v[78:81]
	v_mfma_f32_16x16x32_bf16 v[74:77], v[180:183], v[204:207], v[74:77]
	v_mfma_f32_16x16x32_bf16 v[70:73], v[162:165], v[224:227], v[70:73]
	v_mfma_f32_16x16x32_bf16 v[66:69], v[180:183], v[224:227], v[66:69]
	s_setprio 0
	s_barrier
	s_add_i32 s62, s77, s17
	v_lshl_add_u64 v[168:169], v[168:169], 0, s[54:55]
	s_mov_b32 m0, s62
	ds_read_b128 v[184:187], v140 offset:49152
	ds_read_b128 v[188:191], v140 offset:50176
	ds_read_b128 v[192:195], v140 offset:51200
	ds_read_b128 v[196:199], v140 offset:52224
	ds_read_b128 v[200:203], v140 offset:53248
	ds_read_b128 v[204:207], v140 offset:54272
	ds_read_b128 v[208:211], v140 offset:55296
	ds_read_b128 v[224:227], v140 offset:56320
	global_load_lds_dwordx4 v[168:169], off
	s_add_i32 m0, s62, 0x2000
	s_add_u32 s60, s60, 0x80080
	v_lshl_add_u64 v[168:169], v[212:213], 0, s[54:55]
	s_addc_u32 s61, s61, 0
	s_add_i32 s62, s78, s17
	global_load_lds_dwordx4 v[168:169], off
	v_lshl_add_u64 v[168:169], s[60:61], 0, v[132:133]
	s_mov_b32 m0, s62
	s_nop 0
	global_load_lds_dwordx4 v[168:169], off
	v_lshl_add_u64 v[168:169], s[60:61], 0, v[130:131]
	s_add_i32 m0, s62, 0x2000
	s_nop 0
	global_load_lds_dwordx4 v[168:169], off
	v_lshl_add_u64 v[168:169], v[228:229], 0, s[54:55]
	s_mov_b32 m0, s66
	s_nop 0
	global_load_lds_dwordx4 v[168:169], off
	v_lshl_add_u64 v[168:169], v[230:231], 0, s[54:55]
	s_mov_b32 m0, s67
	s_nop 0
	global_load_lds_dwordx4 v[168:169], off
	s_waitcnt vmcnt(8)
	s_waitcnt lgkmcnt(0)
	s_barrier
	s_setprio 1
	s_waitcnt lgkmcnt(0)
	v_mfma_f32_16x16x32_bf16 v[62:65], v[142:145], v[184:187], v[62:65]
	v_mfma_f32_16x16x32_bf16 v[58:61], v[150:153], v[184:187], v[58:61]
	v_mfma_f32_16x16x32_bf16 v[54:57], v[142:145], v[192:195], v[54:57]
	v_mfma_f32_16x16x32_bf16 v[50:53], v[150:153], v[192:195], v[50:53]
	v_mfma_f32_16x16x32_bf16 v[46:49], v[142:145], v[200:203], v[46:49]
	v_mfma_f32_16x16x32_bf16 v[38:41], v[150:153], v[200:203], v[38:41]
	v_mfma_f32_16x16x32_bf16 v[30:33], v[142:145], v[208:211], v[30:33]
	v_mfma_f32_16x16x32_bf16 v[22:25], v[150:153], v[208:211], v[22:25]
	v_mfma_f32_16x16x32_bf16 v[62:65], v[146:149], v[188:191], v[62:65]
	v_mfma_f32_16x16x32_bf16 v[58:61], v[154:157], v[188:191], v[58:61]
	v_mfma_f32_16x16x32_bf16 v[54:57], v[146:149], v[196:199], v[54:57]
	v_mfma_f32_16x16x32_bf16 v[50:53], v[154:157], v[196:199], v[50:53]
	v_mfma_f32_16x16x32_bf16 v[46:49], v[146:149], v[204:207], v[46:49]
	v_mfma_f32_16x16x32_bf16 v[38:41], v[154:157], v[204:207], v[38:41]
	v_mfma_f32_16x16x32_bf16 v[30:33], v[146:149], v[224:227], v[30:33]
	v_mfma_f32_16x16x32_bf16 v[22:25], v[154:157], v[224:227], v[22:25]
	v_mfma_f32_16x16x32_bf16 v[42:45], v[158:161], v[184:187], v[42:45]
	v_mfma_f32_16x16x32_bf16 v[34:37], v[176:179], v[184:187], v[34:37]
	v_mfma_f32_16x16x32_bf16 v[26:29], v[158:161], v[192:195], v[26:29]
	v_mfma_f32_16x16x32_bf16 v[18:21], v[176:179], v[192:195], v[18:21]
	v_mfma_f32_16x16x32_bf16 v[14:17], v[158:161], v[200:203], v[14:17]
	v_mfma_f32_16x16x32_bf16 v[10:13], v[176:179], v[200:203], v[10:13]
	v_mfma_f32_16x16x32_bf16 v[6:9], v[158:161], v[208:211], v[6:9]
	v_mfma_f32_16x16x32_bf16 v[2:5], v[176:179], v[208:211], v[2:5]
	v_mfma_f32_16x16x32_bf16 v[42:45], v[162:165], v[188:191], v[42:45]
	v_mfma_f32_16x16x32_bf16 v[34:37], v[180:183], v[188:191], v[34:37]
	v_mfma_f32_16x16x32_bf16 v[26:29], v[162:165], v[196:199], v[26:29]
	v_mfma_f32_16x16x32_bf16 v[18:21], v[180:183], v[196:199], v[18:21]
	v_mfma_f32_16x16x32_bf16 v[14:17], v[162:165], v[204:207], v[14:17]
	v_mfma_f32_16x16x32_bf16 v[10:13], v[180:183], v[204:207], v[10:13]
	v_mfma_f32_16x16x32_bf16 v[6:9], v[162:165], v[224:227], v[6:9]
	v_mfma_f32_16x16x32_bf16 v[2:5], v[180:183], v[224:227], v[2:5]
	s_setprio 0
	s_barrier
	s_add_i32 s76, s76, 2
	s_add_u32 s72, s72, 0x100
	s_addc_u32 s73, s73, 0
	s_add_u32 s52, s52, 0x100
	s_addc_u32 s53, s53, 0
	s_cmp_gt_u32 s76, 29
	s_cbranch_scc0 .LBB0_387
	s_and_b64 vcc, exec, s[42:43]
	s_cbranch_vccz .LBB0_390
	s_barrier

.LBB0_408:
	s_add_i32 s81, s52, 2
	s_add_u32 s82, s50, 0x80
	s_addc_u32 s53, s51, 0
	s_add_i32 s84, 0, 0x10000
	s_cmp_eq_u32 s60, s52
	s_cselect_b32 s53, s1, s53
	s_cselect_b32 s52, s0, s82
	v_add_u32_e32 v131, s84, v156
	s_cselect_b32 s83, s43, s80
	s_cselect_b32 s82, s42, s61
	s_add_i32 s85, 0, 0x14000
	ds_read_b128 v[146:149], v131
	ds_read_b128 v[150:153], v131 offset:1024
	ds_read_b128 v[158:161], v131 offset:2048
	ds_read_b128 v[162:165], v131 offset:3072
	v_add_u32_e32 v131, s85, v156
	ds_read_b128 v[176:179], v131
	ds_read_b128 v[180:183], v131 offset:1024
	ds_read_b128 v[184:187], v131 offset:2048
	ds_read_b128 v[188:191], v131 offset:3072
	v_lshl_add_u64 v[154:155], s[50:51], 0, v[144:145]
	s_add_i32 m0, s67, 0xc000
	ds_read_b128 v[192:195], v137
	ds_read_b128 v[196:199], v137 offset:1024
	ds_read_b128 v[200:203], v137 offset:2048
	ds_read_b128 v[204:207], v137 offset:3072
	ds_read_b128 v[208:211], v137 offset:4096
	ds_read_b128 v[224:227], v137 offset:5120
	ds_read_b128 v[228:231], v137 offset:6144
	ds_read_b128 v[232:235], v137 offset:7168
	global_load_lds_dwordx4 v[154:155], off
	v_lshl_add_u64 v[154:155], s[50:51], 0, v[142:143]
	s_add_i32 m0, s67, 0xe000
	s_nop 0
	global_load_lds_dwordx4 v[154:155], off
	s_waitcnt vmcnt(8)
	s_waitcnt lgkmcnt(0)
	s_barrier
	s_setprio 1
	s_waitcnt lgkmcnt(0)
	v_mfma_f32_16x16x32_bf16 v[126:129], v[146:149], v[192:195], v[126:129]
	v_mfma_f32_16x16x32_bf16 v[98:101], v[158:161], v[192:195], v[98:101]
	v_mfma_f32_16x16x32_bf16 v[122:125], v[146:149], v[200:203], v[122:125]
	v_mfma_f32_16x16x32_bf16 v[94:97], v[158:161], v[200:203], v[94:97]
	v_mfma_f32_16x16x32_bf16 v[118:121], v[146:149], v[208:211], v[118:121]
	v_mfma_f32_16x16x32_bf16 v[86:89], v[158:161], v[208:211], v[86:89]
	v_mfma_f32_16x16x32_bf16 v[114:117], v[146:149], v[228:231], v[114:117]
	v_mfma_f32_16x16x32_bf16 v[82:85], v[158:161], v[228:231], v[82:85]
	v_mfma_f32_16x16x32_bf16 v[126:129], v[150:153], v[196:199], v[126:129]
	v_mfma_f32_16x16x32_bf16 v[98:101], v[162:165], v[196:199], v[98:101]
	v_mfma_f32_16x16x32_bf16 v[122:125], v[150:153], v[204:207], v[122:125]
	v_mfma_f32_16x16x32_bf16 v[94:97], v[162:165], v[204:207], v[94:97]
	v_mfma_f32_16x16x32_bf16 v[118:121], v[150:153], v[224:227], v[118:121]
	v_mfma_f32_16x16x32_bf16 v[86:89], v[162:165], v[224:227], v[86:89]
	v_mfma_f32_16x16x32_bf16 v[114:117], v[150:153], v[232:235], v[114:117]
	v_mfma_f32_16x16x32_bf16 v[82:85], v[162:165], v[232:235], v[82:85]
	v_mfma_f32_16x16x32_bf16 v[70:73], v[176:179], v[192:195], v[70:73]
	v_mfma_f32_16x16x32_bf16 v[42:45], v[184:187], v[192:195], v[42:45]
	v_mfma_f32_16x16x32_bf16 v[62:65], v[176:179], v[200:203], v[62:65]
	v_mfma_f32_16x16x32_bf16 v[34:37], v[184:187], v[200:203], v[34:37]
	v_mfma_f32_16x16x32_bf16 v[54:57], v[176:179], v[208:211], v[54:57]
	v_mfma_f32_16x16x32_bf16 v[26:29], v[184:187], v[208:211], v[26:29]
	v_mfma_f32_16x16x32_bf16 v[50:53], v[176:179], v[228:231], v[50:53]
	v_mfma_f32_16x16x32_bf16 v[18:21], v[184:187], v[228:231], v[18:21]
	v_mfma_f32_16x16x32_bf16 v[70:73], v[180:183], v[196:199], v[70:73]
	v_mfma_f32_16x16x32_bf16 v[42:45], v[188:191], v[196:199], v[42:45]
	v_mfma_f32_16x16x32_bf16 v[62:65], v[180:183], v[204:207], v[62:65]
	v_mfma_f32_16x16x32_bf16 v[34:37], v[188:191], v[204:207], v[34:37]
	v_mfma_f32_16x16x32_bf16 v[54:57], v[180:183], v[224:227], v[54:57]
	v_mfma_f32_16x16x32_bf16 v[26:29], v[188:191], v[224:227], v[26:29]
	v_mfma_f32_16x16x32_bf16 v[50:53], v[180:183], v[232:235], v[50:53]
	v_mfma_f32_16x16x32_bf16 v[18:21], v[188:191], v[232:235], v[18:21]
	s_setprio 0
	s_barrier
	s_add_i32 s84, s84, s65
	v_lshl_add_u64 v[154:155], s[82:83], 0, v[134:135]
	s_mov_b32 m0, s84
	ds_read_b128 v[192:195], v137 offset:16384
	ds_read_b128 v[196:199], v137 offset:17408
	ds_read_b128 v[200:203], v137 offset:18432
	ds_read_b128 v[204:207], v137 offset:19456
	ds_read_b128 v[208:211], v137 offset:20480
	ds_read_b128 v[224:227], v137 offset:21504
	ds_read_b128 v[228:231], v137 offset:22528
	ds_read_b128 v[232:235], v137 offset:23552
	global_load_lds_dwordx4 v[154:155], off
	s_add_i32 m0, s84, 0x2000
	v_lshl_add_u64 v[168:169], s[82:83], 0, v[132:133]
	s_add_u32 s82, s82, s26
	s_addc_u32 s83, s83, 0
	s_add_i32 s84, s85, s65
	global_load_lds_dwordx4 v[168:169], off
	v_lshl_add_u64 v[212:213], s[82:83], 0, v[134:135]
	s_mov_b32 m0, s84
	v_lshl_add_u64 v[236:237], s[82:83], 0, v[132:133]
	global_load_lds_dwordx4 v[212:213], off
	s_add_i32 m0, s84, 0x2000
	v_lshl_add_u64 v[238:239], s[52:53], 0, v[134:135]
	global_load_lds_dwordx4 v[236:237], off
	s_mov_b32 m0, s67
	v_lshl_add_u64 v[244:245], s[52:53], 0, v[132:133]
	global_load_lds_dwordx4 v[238:239], off
	s_mov_b32 m0, s68
	s_nop 0
	global_load_lds_dwordx4 v[244:245], off
	s_waitcnt vmcnt(8)
	s_waitcnt lgkmcnt(0)
	s_barrier
	s_setprio 1
	s_waitcnt lgkmcnt(0)
	v_mfma_f32_16x16x32_bf16 v[110:113], v[146:149], v[192:195], v[110:113]
	v_mfma_f32_16x16x32_bf16 v[78:81], v[158:161], v[192:195], v[78:81]
	v_mfma_f32_16x16x32_bf16 v[106:109], v[146:149], v[200:203], v[106:109]
	v_mfma_f32_16x16x32_bf16 v[74:77], v[158:161], v[200:203], v[74:77]
	v_mfma_f32_16x16x32_bf16 v[102:105], v[146:149], v[208:211], v[102:105]
	v_mfma_f32_16x16x32_bf16 v[66:69], v[158:161], v[208:211], v[66:69]
	v_mfma_f32_16x16x32_bf16 v[90:93], v[146:149], v[228:231], v[90:93]
	v_mfma_f32_16x16x32_bf16 v[58:61], v[158:161], v[228:231], v[58:61]
	v_mfma_f32_16x16x32_bf16 v[110:113], v[150:153], v[196:199], v[110:113]
	v_mfma_f32_16x16x32_bf16 v[78:81], v[162:165], v[196:199], v[78:81]
	v_mfma_f32_16x16x32_bf16 v[106:109], v[150:153], v[204:207], v[106:109]
	v_mfma_f32_16x16x32_bf16 v[74:77], v[162:165], v[204:207], v[74:77]
	v_mfma_f32_16x16x32_bf16 v[102:105], v[150:153], v[224:227], v[102:105]
	v_mfma_f32_16x16x32_bf16 v[66:69], v[162:165], v[224:227], v[66:69]
	v_mfma_f32_16x16x32_bf16 v[90:93], v[150:153], v[232:235], v[90:93]
	v_mfma_f32_16x16x32_bf16 v[58:61], v[162:165], v[232:235], v[58:61]
	v_mfma_f32_16x16x32_bf16 v[46:49], v[176:179], v[192:195], v[46:49]
	v_mfma_f32_16x16x32_bf16 v[14:17], v[184:187], v[192:195], v[14:17]
	v_mfma_f32_16x16x32_bf16 v[38:41], v[176:179], v[200:203], v[38:41]
	v_mfma_f32_16x16x32_bf16 v[10:13], v[184:187], v[200:203], v[10:13]
	v_mfma_f32_16x16x32_bf16 v[30:33], v[176:179], v[208:211], v[30:33]
	v_mfma_f32_16x16x32_bf16 v[6:9], v[184:187], v[208:211], v[6:9]
	v_mfma_f32_16x16x32_bf16 v[22:25], v[176:179], v[228:231], v[22:25]
	v_mfma_f32_16x16x32_bf16 v[2:5], v[184:187], v[228:231], v[2:5]
	v_mfma_f32_16x16x32_bf16 v[46:49], v[180:183], v[196:199], v[46:49]
	v_mfma_f32_16x16x32_bf16 v[14:17], v[188:191], v[196:199], v[14:17]
	v_mfma_f32_16x16x32_bf16 v[38:41], v[180:183], v[204:207], v[38:41]
	v_mfma_f32_16x16x32_bf16 v[10:13], v[188:191], v[204:207], v[10:13]
	v_mfma_f32_16x16x32_bf16 v[30:33], v[180:183], v[224:227], v[30:33]
	v_mfma_f32_16x16x32_bf16 v[6:9], v[188:191], v[224:227], v[6:9]
	v_mfma_f32_16x16x32_bf16 v[22:25], v[180:183], v[232:235], v[22:25]
	v_mfma_f32_16x16x32_bf16 v[2:5], v[188:191], v[232:235], v[2:5]
	s_setprio 0
	s_barrier
	s_add_i32 s82, 0, 0x18000
	v_add_u32_e32 v131, s82, v156
	s_add_i32 s83, 0, 0x1c000
	ds_read_b128 v[146:149], v131
	ds_read_b128 v[150:153], v131 offset:1024
	ds_read_b128 v[158:161], v131 offset:2048
	ds_read_b128 v[162:165], v131 offset:3072
	v_add_u32_e32 v131, s83, v156
	ds_read_b128 v[176:179], v131
	ds_read_b128 v[180:183], v131 offset:1024
	ds_read_b128 v[184:187], v131 offset:2048
	ds_read_b128 v[188:191], v131 offset:3072
	s_add_u32 s52, s52, s26
	s_addc_u32 s53, s53, 0
	s_mov_b32 m0, s69
	v_lshl_add_u64 v[246:247], s[52:53], 0, v[134:135]
	ds_read_b128 v[192:195], v137 offset:32768
	ds_read_b128 v[196:199], v137 offset:33792
	ds_read_b128 v[200:203], v137 offset:34816
	ds_read_b128 v[204:207], v137 offset:35840
	ds_read_b128 v[208:211], v137 offset:36864
	ds_read_b128 v[224:227], v137 offset:37888
	ds_read_b128 v[228:231], v137 offset:38912
	ds_read_b128 v[232:235], v137 offset:39936
	global_load_lds_dwordx4 v[246:247], off
	v_lshl_add_u64 v[246:247], s[52:53], 0, v[132:133]
	s_mov_b32 m0, s70
	s_nop 0
	global_load_lds_dwordx4 v[246:247], off
	s_waitcnt vmcnt(8)
	s_waitcnt lgkmcnt(0)
	s_barrier
	s_setprio 1
	s_waitcnt lgkmcnt(0)
	v_mfma_f32_16x16x32_bf16 v[126:129], v[146:149], v[192:195], v[126:129]
	v_mfma_f32_16x16x32_bf16 v[98:101], v[158:161], v[192:195], v[98:101]
	v_mfma_f32_16x16x32_bf16 v[122:125], v[146:149], v[200:203], v[122:125]
	v_mfma_f32_16x16x32_bf16 v[94:97], v[158:161], v[200:203], v[94:97]
	v_mfma_f32_16x16x32_bf16 v[118:121], v[146:149], v[208:211], v[118:121]
	v_mfma_f32_16x16x32_bf16 v[86:89], v[158:161], v[208:211], v[86:89]
	v_mfma_f32_16x16x32_bf16 v[114:117], v[146:149], v[228:231], v[114:117]
	v_mfma_f32_16x16x32_bf16 v[82:85], v[158:161], v[228:231], v[82:85]
	v_mfma_f32_16x16x32_bf16 v[126:129], v[150:153], v[196:199], v[126:129]
	v_mfma_f32_16x16x32_bf16 v[98:101], v[162:165], v[196:199], v[98:101]
	v_mfma_f32_16x16x32_bf16 v[122:125], v[150:153], v[204:207], v[122:125]
	v_mfma_f32_16x16x32_bf16 v[94:97], v[162:165], v[204:207], v[94:97]
	v_mfma_f32_16x16x32_bf16 v[118:121], v[150:153], v[224:227], v[118:121]
	v_mfma_f32_16x16x32_bf16 v[86:89], v[162:165], v[224:227], v[86:89]
	v_mfma_f32_16x16x32_bf16 v[114:117], v[150:153], v[232:235], v[114:117]
	v_mfma_f32_16x16x32_bf16 v[82:85], v[162:165], v[232:235], v[82:85]
	v_mfma_f32_16x16x32_bf16 v[70:73], v[176:179], v[192:195], v[70:73]
	v_mfma_f32_16x16x32_bf16 v[42:45], v[184:187], v[192:195], v[42:45]
	v_mfma_f32_16x16x32_bf16 v[62:65], v[176:179], v[200:203], v[62:65]
	v_mfma_f32_16x16x32_bf16 v[34:37], v[184:187], v[200:203], v[34:37]
	v_mfma_f32_16x16x32_bf16 v[54:57], v[176:179], v[208:211], v[54:57]
	v_mfma_f32_16x16x32_bf16 v[26:29], v[184:187], v[208:211], v[26:29]
	v_mfma_f32_16x16x32_bf16 v[50:53], v[176:179], v[228:231], v[50:53]
	v_mfma_f32_16x16x32_bf16 v[18:21], v[184:187], v[228:231], v[18:21]
	v_mfma_f32_16x16x32_bf16 v[70:73], v[180:183], v[196:199], v[70:73]
	v_mfma_f32_16x16x32_bf16 v[42:45], v[188:191], v[196:199], v[42:45]
	v_mfma_f32_16x16x32_bf16 v[62:65], v[180:183], v[204:207], v[62:65]
	v_mfma_f32_16x16x32_bf16 v[34:37], v[188:191], v[204:207], v[34:37]
	v_mfma_f32_16x16x32_bf16 v[54:57], v[180:183], v[224:227], v[54:57]
	v_mfma_f32_16x16x32_bf16 v[26:29], v[188:191], v[224:227], v[26:29]
	v_mfma_f32_16x16x32_bf16 v[50:53], v[180:183], v[232:235], v[50:53]
	v_mfma_f32_16x16x32_bf16 v[18:21], v[188:191], v[232:235], v[18:21]
	s_setprio 0
	s_barrier
	s_add_i32 s52, s82, s65
	v_lshl_add_u64 v[154:155], v[154:155], 0, s[54:55]
	s_mov_b32 m0, s52
	ds_read_b128 v[192:195], v137 offset:49152
	ds_read_b128 v[196:199], v137 offset:50176
	ds_read_b128 v[200:203], v137 offset:51200
	ds_read_b128 v[204:207], v137 offset:52224
	ds_read_b128 v[208:211], v137 offset:53248
	ds_read_b128 v[224:227], v137 offset:54272
	ds_read_b128 v[228:231], v137 offset:55296
	ds_read_b128 v[232:235], v137 offset:56320
	global_load_lds_dwordx4 v[154:155], off
	v_lshl_add_u64 v[154:155], v[168:169], 0, s[54:55]
	s_add_i32 m0, s52, 0x2000
	s_add_i32 s52, s83, s65
	global_load_lds_dwordx4 v[154:155], off
	v_lshl_add_u64 v[154:155], v[212:213], 0, s[54:55]
	s_mov_b32 m0, s52
	s_nop 0
	global_load_lds_dwordx4 v[154:155], off
	v_lshl_add_u64 v[154:155], v[236:237], 0, s[54:55]
	s_add_i32 m0, s52, 0x2000
	s_nop 0
	global_load_lds_dwordx4 v[154:155], off
	v_lshl_add_u64 v[154:155], v[238:239], 0, s[54:55]
	s_mov_b32 m0, s71
	s_nop 0
	global_load_lds_dwordx4 v[154:155], off
	v_lshl_add_u64 v[154:155], v[244:245], 0, s[54:55]
	s_mov_b32 m0, s72
	s_nop 0
	global_load_lds_dwordx4 v[154:155], off
	s_waitcnt vmcnt(8)
	s_waitcnt lgkmcnt(0)
	s_barrier
	s_setprio 1
	s_waitcnt lgkmcnt(0)
	v_mfma_f32_16x16x32_bf16 v[110:113], v[146:149], v[192:195], v[110:113]
	v_mfma_f32_16x16x32_bf16 v[78:81], v[158:161], v[192:195], v[78:81]
	v_mfma_f32_16x16x32_bf16 v[106:109], v[146:149], v[200:203], v[106:109]
	v_mfma_f32_16x16x32_bf16 v[74:77], v[158:161], v[200:203], v[74:77]
	v_mfma_f32_16x16x32_bf16 v[102:105], v[146:149], v[208:211], v[102:105]
	v_mfma_f32_16x16x32_bf16 v[66:69], v[158:161], v[208:211], v[66:69]
	v_mfma_f32_16x16x32_bf16 v[90:93], v[146:149], v[228:231], v[90:93]
	v_mfma_f32_16x16x32_bf16 v[58:61], v[158:161], v[228:231], v[58:61]
	v_mfma_f32_16x16x32_bf16 v[110:113], v[150:153], v[196:199], v[110:113]
	v_mfma_f32_16x16x32_bf16 v[78:81], v[162:165], v[196:199], v[78:81]
	v_mfma_f32_16x16x32_bf16 v[106:109], v[150:153], v[204:207], v[106:109]
	v_mfma_f32_16x16x32_bf16 v[74:77], v[162:165], v[204:207], v[74:77]
	v_mfma_f32_16x16x32_bf16 v[102:105], v[150:153], v[224:227], v[102:105]
	v_mfma_f32_16x16x32_bf16 v[66:69], v[162:165], v[224:227], v[66:69]
	v_mfma_f32_16x16x32_bf16 v[90:93], v[150:153], v[232:235], v[90:93]
	v_mfma_f32_16x16x32_bf16 v[58:61], v[162:165], v[232:235], v[58:61]
	v_mfma_f32_16x16x32_bf16 v[46:49], v[176:179], v[192:195], v[46:49]
	v_mfma_f32_16x16x32_bf16 v[14:17], v[184:187], v[192:195], v[14:17]
	v_mfma_f32_16x16x32_bf16 v[38:41], v[176:179], v[200:203], v[38:41]
	v_mfma_f32_16x16x32_bf16 v[10:13], v[184:187], v[200:203], v[10:13]
	v_mfma_f32_16x16x32_bf16 v[30:33], v[176:179], v[208:211], v[30:33]
	v_mfma_f32_16x16x32_bf16 v[6:9], v[184:187], v[208:211], v[6:9]
	v_mfma_f32_16x16x32_bf16 v[22:25], v[176:179], v[228:231], v[22:25]
	v_mfma_f32_16x16x32_bf16 v[2:5], v[184:187], v[228:231], v[2:5]
	v_mfma_f32_16x16x32_bf16 v[46:49], v[180:183], v[196:199], v[46:49]
	v_mfma_f32_16x16x32_bf16 v[14:17], v[188:191], v[196:199], v[14:17]
	v_mfma_f32_16x16x32_bf16 v[38:41], v[180:183], v[204:207], v[38:41]
	v_mfma_f32_16x16x32_bf16 v[10:13], v[188:191], v[204:207], v[10:13]
	v_mfma_f32_16x16x32_bf16 v[30:33], v[180:183], v[224:227], v[30:33]
	v_mfma_f32_16x16x32_bf16 v[6:9], v[188:191], v[224:227], v[6:9]
	v_mfma_f32_16x16x32_bf16 v[22:25], v[180:183], v[232:235], v[22:25]
	v_mfma_f32_16x16x32_bf16 v[2:5], v[188:191], v[232:235], v[2:5]
	s_setprio 0
	s_barrier
	s_add_u32 s61, s61, 0x100
	s_addc_u32 s80, s80, 0
	s_add_u32 s50, s50, 0x100
	s_addc_u32 s51, s51, 0
	s_cmp_ge_i32 s81, s64
	s_mov_b32 s52, s81
	s_cbranch_scc0 .LBB0_408
	s_cmp_lt_i32 s78, 32
	s_cselect_b64 s[52:53], -1, 0
	s_mov_b64 s[50:51], 0
	s_and_b64 vcc, exec, s[52:53]
	s_mov_b64 s[60:61], s[46:47]
	s_cbranch_vccnz .LBB0_400
	s_sub_i32 s50, s78, 32
	s_lshr_b32 s50, s50, 2
	s_add_i32 s50, s50, 1
	s_mul_hi_u32 s51, s50, 0x4800
	s_mulk_i32 s50, 0x4800
	s_mov_b64 s[60:61], s[24:25]
	s_branch .LBB0_400

.LBB0_432:
	s_add_i32 s76, 0, 0x10000
	v_add_u32_e32 v142, s76, v145
	s_add_i32 s78, 0, 0x14000
	ds_read_b128 v[154:157], v142
	ds_read_b128 v[158:161], v142 offset:1024
	ds_read_b128 v[162:165], v142 offset:2048
	ds_read_b128 v[176:179], v142 offset:3072
	v_add_u32_e32 v142, s78, v145
	ds_read_b128 v[180:183], v142
	ds_read_b128 v[184:187], v142 offset:1024
	ds_read_b128 v[188:191], v142 offset:2048
	ds_read_b128 v[192:195], v142 offset:3072
	v_lshl_add_u64 v[142:143], s[50:51], 0, v[140:141]
	s_add_i32 m0, s66, 0xc000
	ds_read_b128 v[196:199], v153
	ds_read_b128 v[200:203], v153 offset:1024
	ds_read_b128 v[204:207], v153 offset:2048
	ds_read_b128 v[208:211], v153 offset:3072
	ds_read_b128 v[224:227], v153 offset:4096
	ds_read_b128 v[228:231], v153 offset:5120
	ds_read_b128 v[232:235], v153 offset:6144
	ds_read_b128 v[236:239], v153 offset:7168
	global_load_lds_dwordx4 v[142:143], off
	v_lshl_add_u64 v[142:143], s[50:51], 0, v[138:139]
	s_add_i32 m0, s66, 0xe000
	s_nop 0
	global_load_lds_dwordx4 v[142:143], off
	s_waitcnt vmcnt(8)
	s_waitcnt lgkmcnt(0)
	s_barrier
	s_setprio 1
	s_waitcnt lgkmcnt(0)
	v_mfma_f32_16x16x32_bf16 v[126:129], v[154:157], v[196:199], v[126:129]
	v_mfma_f32_16x16x32_bf16 v[118:121], v[162:165], v[196:199], v[118:121]
	v_mfma_f32_16x16x32_bf16 v[110:113], v[154:157], v[204:207], v[110:113]
	v_mfma_f32_16x16x32_bf16 v[102:105], v[162:165], v[204:207], v[102:105]
	v_mfma_f32_16x16x32_bf16 v[94:97], v[154:157], v[224:227], v[94:97]
	v_mfma_f32_16x16x32_bf16 v[86:89], v[162:165], v[224:227], v[86:89]
	v_mfma_f32_16x16x32_bf16 v[78:81], v[154:157], v[232:235], v[78:81]
	v_mfma_f32_16x16x32_bf16 v[70:73], v[162:165], v[232:235], v[70:73]
	v_mfma_f32_16x16x32_bf16 v[126:129], v[158:161], v[200:203], v[126:129]
	v_mfma_f32_16x16x32_bf16 v[118:121], v[176:179], v[200:203], v[118:121]
	v_mfma_f32_16x16x32_bf16 v[110:113], v[158:161], v[208:211], v[110:113]
	v_mfma_f32_16x16x32_bf16 v[102:105], v[176:179], v[208:211], v[102:105]
	v_mfma_f32_16x16x32_bf16 v[94:97], v[158:161], v[228:231], v[94:97]
	v_mfma_f32_16x16x32_bf16 v[86:89], v[176:179], v[228:231], v[86:89]
	v_mfma_f32_16x16x32_bf16 v[78:81], v[158:161], v[236:239], v[78:81]
	v_mfma_f32_16x16x32_bf16 v[70:73], v[176:179], v[236:239], v[70:73]
	v_mfma_f32_16x16x32_bf16 v[122:125], v[180:183], v[196:199], v[122:125]
	v_mfma_f32_16x16x32_bf16 v[114:117], v[188:191], v[196:199], v[114:117]
	v_mfma_f32_16x16x32_bf16 v[106:109], v[180:183], v[204:207], v[106:109]
	v_mfma_f32_16x16x32_bf16 v[98:101], v[188:191], v[204:207], v[98:101]
	v_mfma_f32_16x16x32_bf16 v[90:93], v[180:183], v[224:227], v[90:93]
	v_mfma_f32_16x16x32_bf16 v[82:85], v[188:191], v[224:227], v[82:85]
	v_mfma_f32_16x16x32_bf16 v[74:77], v[180:183], v[232:235], v[74:77]
	v_mfma_f32_16x16x32_bf16 v[66:69], v[188:191], v[232:235], v[66:69]
	v_mfma_f32_16x16x32_bf16 v[122:125], v[184:187], v[200:203], v[122:125]
	v_mfma_f32_16x16x32_bf16 v[114:117], v[192:195], v[200:203], v[114:117]
	v_mfma_f32_16x16x32_bf16 v[106:109], v[184:187], v[208:211], v[106:109]
	v_mfma_f32_16x16x32_bf16 v[98:101], v[192:195], v[208:211], v[98:101]
	v_mfma_f32_16x16x32_bf16 v[90:93], v[184:187], v[228:231], v[90:93]
	v_mfma_f32_16x16x32_bf16 v[82:85], v[192:195], v[228:231], v[82:85]
	v_mfma_f32_16x16x32_bf16 v[74:77], v[184:187], v[236:239], v[74:77]
	v_mfma_f32_16x16x32_bf16 v[66:69], v[192:195], v[236:239], v[66:69]
	s_setprio 0
	s_barrier
	s_add_i32 s76, s76, s64
	v_lshl_add_u64 v[142:143], s[52:53], 0, v[134:135]
	s_mov_b32 m0, s76
	ds_read_b128 v[196:199], v153 offset:16384
	ds_read_b128 v[200:203], v153 offset:17408
	ds_read_b128 v[204:207], v153 offset:18432
	ds_read_b128 v[208:211], v153 offset:19456
	ds_read_b128 v[224:227], v153 offset:20480
	ds_read_b128 v[228:231], v153 offset:21504
	ds_read_b128 v[232:235], v153 offset:22528
	ds_read_b128 v[236:239], v153 offset:23552
	global_load_lds_dwordx4 v[142:143], off
	s_add_i32 m0, s76, 0x2000
	s_add_u32 s76, s52, 0x80000
	v_lshl_add_u64 v[168:169], s[52:53], 0, v[130:131]
	s_addc_u32 s77, s53, 0
	s_add_i32 s78, s78, s64
	global_load_lds_dwordx4 v[168:169], off
	v_lshl_add_u64 v[212:213], s[76:77], 0, v[134:135]
	s_mov_b32 m0, s78
	v_lshl_add_u64 v[244:245], s[60:61], 0, v[132:133]
	global_load_lds_dwordx4 v[212:213], off
	v_lshl_add_u64 v[212:213], s[76:77], 0, v[130:131]
	s_add_i32 m0, s78, 0x2000
	s_nop 0
	global_load_lds_dwordx4 v[212:213], off
	v_lshl_add_u64 v[212:213], s[60:61], 0, v[136:137]
	s_mov_b32 m0, s66
	s_nop 0
	global_load_lds_dwordx4 v[212:213], off
	s_mov_b32 m0, s67
	s_nop 0
	global_load_lds_dwordx4 v[244:245], off
	s_waitcnt vmcnt(8)
	s_waitcnt lgkmcnt(0)
	s_barrier
	s_setprio 1
	s_waitcnt lgkmcnt(0)
	v_mfma_f32_16x16x32_bf16 v[62:65], v[154:157], v[196:199], v[62:65]
	v_mfma_f32_16x16x32_bf16 v[54:57], v[162:165], v[196:199], v[54:57]
	v_mfma_f32_16x16x32_bf16 v[46:49], v[154:157], v[204:207], v[46:49]
	v_mfma_f32_16x16x32_bf16 v[38:41], v[162:165], v[204:207], v[38:41]
	v_mfma_f32_16x16x32_bf16 v[30:33], v[154:157], v[224:227], v[30:33]
	v_mfma_f32_16x16x32_bf16 v[22:25], v[162:165], v[224:227], v[22:25]
	v_mfma_f32_16x16x32_bf16 v[14:17], v[154:157], v[232:235], v[14:17]
	v_mfma_f32_16x16x32_bf16 v[6:9], v[162:165], v[232:235], v[6:9]
	v_mfma_f32_16x16x32_bf16 v[62:65], v[158:161], v[200:203], v[62:65]
	v_mfma_f32_16x16x32_bf16 v[54:57], v[176:179], v[200:203], v[54:57]
	v_mfma_f32_16x16x32_bf16 v[46:49], v[158:161], v[208:211], v[46:49]
	v_mfma_f32_16x16x32_bf16 v[38:41], v[176:179], v[208:211], v[38:41]
	v_mfma_f32_16x16x32_bf16 v[30:33], v[158:161], v[228:231], v[30:33]
	v_mfma_f32_16x16x32_bf16 v[22:25], v[176:179], v[228:231], v[22:25]
	v_mfma_f32_16x16x32_bf16 v[14:17], v[158:161], v[236:239], v[14:17]
	v_mfma_f32_16x16x32_bf16 v[6:9], v[176:179], v[236:239], v[6:9]
	v_mfma_f32_16x16x32_bf16 v[58:61], v[180:183], v[196:199], v[58:61]
	v_mfma_f32_16x16x32_bf16 v[50:53], v[188:191], v[196:199], v[50:53]
	v_mfma_f32_16x16x32_bf16 v[42:45], v[180:183], v[204:207], v[42:45]
	v_mfma_f32_16x16x32_bf16 v[34:37], v[188:191], v[204:207], v[34:37]
	v_mfma_f32_16x16x32_bf16 v[26:29], v[180:183], v[224:227], v[26:29]
	v_mfma_f32_16x16x32_bf16 v[18:21], v[188:191], v[224:227], v[18:21]
	v_mfma_f32_16x16x32_bf16 v[10:13], v[180:183], v[232:235], v[10:13]
	v_mfma_f32_16x16x32_bf16 v[2:5], v[188:191], v[232:235], v[2:5]
	v_mfma_f32_16x16x32_bf16 v[58:61], v[184:187], v[200:203], v[58:61]
	v_mfma_f32_16x16x32_bf16 v[50:53], v[192:195], v[200:203], v[50:53]
	v_mfma_f32_16x16x32_bf16 v[42:45], v[184:187], v[208:211], v[42:45]
	v_mfma_f32_16x16x32_bf16 v[34:37], v[192:195], v[208:211], v[34:37]
	v_mfma_f32_16x16x32_bf16 v[26:29], v[184:187], v[228:231], v[26:29]
	v_mfma_f32_16x16x32_bf16 v[18:21], v[192:195], v[228:231], v[18:21]
	v_mfma_f32_16x16x32_bf16 v[10:13], v[184:187], v[236:239], v[10:13]
	v_mfma_f32_16x16x32_bf16 v[2:5], v[192:195], v[236:239], v[2:5]
	s_setprio 0
	s_barrier
	s_add_i32 s76, 0, 0x18000
	v_add_u32_e32 v170, s76, v145
	s_add_i32 s77, 0, 0x1c000
	ds_read_b128 v[154:157], v170
	ds_read_b128 v[158:161], v170 offset:1024
	ds_read_b128 v[162:165], v170 offset:2048
	ds_read_b128 v[176:179], v170 offset:3072
	v_add_u32_e32 v170, s77, v145
	ds_read_b128 v[180:183], v170
	ds_read_b128 v[184:187], v170 offset:1024
	ds_read_b128 v[188:191], v170 offset:2048
	ds_read_b128 v[192:195], v170 offset:3072
	s_add_u32 s60, s60, 0x80000
	s_addc_u32 s61, s61, 0
	s_mov_b32 m0, s68
	v_lshl_add_u64 v[246:247], s[60:61], 0, v[136:137]
	ds_read_b128 v[196:199], v153 offset:32768
	ds_read_b128 v[200:203], v153 offset:33792
	ds_read_b128 v[204:207], v153 offset:34816
	ds_read_b128 v[208:211], v153 offset:35840
	ds_read_b128 v[224:227], v153 offset:36864
	ds_read_b128 v[228:231], v153 offset:37888
	ds_read_b128 v[232:235], v153 offset:38912
	ds_read_b128 v[236:239], v153 offset:39936
	global_load_lds_dwordx4 v[246:247], off
	v_lshl_add_u64 v[246:247], s[60:61], 0, v[132:133]
	s_mov_b32 m0, s69
	s_nop 0
	global_load_lds_dwordx4 v[246:247], off
	s_waitcnt vmcnt(8)
	s_waitcnt lgkmcnt(0)
	s_barrier
	s_setprio 1
	s_waitcnt lgkmcnt(0)
	v_mfma_f32_16x16x32_bf16 v[126:129], v[154:157], v[196:199], v[126:129]
	v_mfma_f32_16x16x32_bf16 v[118:121], v[162:165], v[196:199], v[118:121]
	v_mfma_f32_16x16x32_bf16 v[110:113], v[154:157], v[204:207], v[110:113]
	v_mfma_f32_16x16x32_bf16 v[102:105], v[162:165], v[204:207], v[102:105]
	v_mfma_f32_16x16x32_bf16 v[94:97], v[154:157], v[224:227], v[94:97]
	v_mfma_f32_16x16x32_bf16 v[86:89], v[162:165], v[224:227], v[86:89]
	v_mfma_f32_16x16x32_bf16 v[78:81], v[154:157], v[232:235], v[78:81]
	v_mfma_f32_16x16x32_bf16 v[70:73], v[162:165], v[232:235], v[70:73]
	v_mfma_f32_16x16x32_bf16 v[126:129], v[158:161], v[200:203], v[126:129]
	v_mfma_f32_16x16x32_bf16 v[118:121], v[176:179], v[200:203], v[118:121]
	v_mfma_f32_16x16x32_bf16 v[110:113], v[158:161], v[208:211], v[110:113]
	v_mfma_f32_16x16x32_bf16 v[102:105], v[176:179], v[208:211], v[102:105]
	v_mfma_f32_16x16x32_bf16 v[94:97], v[158:161], v[228:231], v[94:97]
	v_mfma_f32_16x16x32_bf16 v[86:89], v[176:179], v[228:231], v[86:89]
	v_mfma_f32_16x16x32_bf16 v[78:81], v[158:161], v[236:239], v[78:81]
	v_mfma_f32_16x16x32_bf16 v[70:73], v[176:179], v[236:239], v[70:73]
	v_mfma_f32_16x16x32_bf16 v[122:125], v[180:183], v[196:199], v[122:125]
	v_mfma_f32_16x16x32_bf16 v[114:117], v[188:191], v[196:199], v[114:117]
	v_mfma_f32_16x16x32_bf16 v[106:109], v[180:183], v[204:207], v[106:109]
	v_mfma_f32_16x16x32_bf16 v[98:101], v[188:191], v[204:207], v[98:101]
	v_mfma_f32_16x16x32_bf16 v[90:93], v[180:183], v[224:227], v[90:93]
	v_mfma_f32_16x16x32_bf16 v[82:85], v[188:191], v[224:227], v[82:85]
	v_mfma_f32_16x16x32_bf16 v[74:77], v[180:183], v[232:235], v[74:77]
	v_mfma_f32_16x16x32_bf16 v[66:69], v[188:191], v[232:235], v[66:69]
	v_mfma_f32_16x16x32_bf16 v[122:125], v[184:187], v[200:203], v[122:125]
	v_mfma_f32_16x16x32_bf16 v[114:117], v[192:195], v[200:203], v[114:117]
	v_mfma_f32_16x16x32_bf16 v[106:109], v[184:187], v[208:211], v[106:109]
	v_mfma_f32_16x16x32_bf16 v[98:101], v[192:195], v[208:211], v[98:101]
	v_mfma_f32_16x16x32_bf16 v[90:93], v[184:187], v[228:231], v[90:93]
	v_mfma_f32_16x16x32_bf16 v[82:85], v[192:195], v[228:231], v[82:85]
	v_mfma_f32_16x16x32_bf16 v[74:77], v[184:187], v[236:239], v[74:77]
	v_mfma_f32_16x16x32_bf16 v[66:69], v[192:195], v[236:239], v[66:69]
	s_setprio 0
	s_barrier
	s_add_i32 s60, s76, s64
	v_lshl_add_u64 v[142:143], v[142:143], 0, s[54:55]
	s_mov_b32 m0, s60
	ds_read_b128 v[196:199], v153 offset:49152
	ds_read_b128 v[200:203], v153 offset:50176
	ds_read_b128 v[204:207], v153 offset:51200
	ds_read_b128 v[208:211], v153 offset:52224
	ds_read_b128 v[224:227], v153 offset:53248
	ds_read_b128 v[228:231], v153 offset:54272
	ds_read_b128 v[232:235], v153 offset:55296
	ds_read_b128 v[236:239], v153 offset:56320
	global_load_lds_dwordx4 v[142:143], off
	s_add_i32 m0, s60, 0x2000
	s_add_u32 s52, s52, 0x80080
	v_lshl_add_u64 v[142:143], v[168:169], 0, s[54:55]
	s_addc_u32 s53, s53, 0
	s_add_i32 s60, s77, s64
	global_load_lds_dwordx4 v[142:143], off
	v_lshl_add_u64 v[142:143], s[52:53], 0, v[134:135]
	s_mov_b32 m0, s60
	s_nop 0
	global_load_lds_dwordx4 v[142:143], off
	v_lshl_add_u64 v[142:143], s[52:53], 0, v[130:131]
	s_add_i32 m0, s60, 0x2000
	s_nop 0
	global_load_lds_dwordx4 v[142:143], off
	v_lshl_add_u64 v[142:143], v[212:213], 0, s[54:55]
	s_mov_b32 m0, s70
	s_nop 0
	global_load_lds_dwordx4 v[142:143], off
	v_lshl_add_u64 v[142:143], v[244:245], 0, s[54:55]
	s_mov_b32 m0, s71
	s_nop 0
	global_load_lds_dwordx4 v[142:143], off
	s_add_i32 s73, s73, 2
	s_add_u32 s43, s43, 0x100
	s_addc_u32 s49, s49, 0
	s_add_u32 s50, s50, 0x100
	s_addc_u32 s51, s51, 0
	s_add_u32 s52, s50, 0xfff80080
	s_addc_u32 s53, s51, -1
	s_cmp_eq_u32 s73, 28
	s_cselect_b32 s61, s6, s53
	s_cselect_b32 s60, s14, s52
	s_cselect_b32 s53, s17, s49
	s_cselect_b32 s52, s41, s43
	s_waitcnt vmcnt(8)
	s_waitcnt lgkmcnt(0)
	s_barrier
	s_setprio 1
	s_waitcnt lgkmcnt(0)
	v_mfma_f32_16x16x32_bf16 v[62:65], v[154:157], v[196:199], v[62:65]
	v_mfma_f32_16x16x32_bf16 v[54:57], v[162:165], v[196:199], v[54:57]
	v_mfma_f32_16x16x32_bf16 v[46:49], v[154:157], v[204:207], v[46:49]
	v_mfma_f32_16x16x32_bf16 v[38:41], v[162:165], v[204:207], v[38:41]
	v_mfma_f32_16x16x32_bf16 v[30:33], v[154:157], v[224:227], v[30:33]
	v_mfma_f32_16x16x32_bf16 v[22:25], v[162:165], v[224:227], v[22:25]
	v_mfma_f32_16x16x32_bf16 v[14:17], v[154:157], v[232:235], v[14:17]
	v_mfma_f32_16x16x32_bf16 v[6:9], v[162:165], v[232:235], v[6:9]
	v_mfma_f32_16x16x32_bf16 v[62:65], v[158:161], v[200:203], v[62:65]
	v_mfma_f32_16x16x32_bf16 v[54:57], v[176:179], v[200:203], v[54:57]
	v_mfma_f32_16x16x32_bf16 v[46:49], v[158:161], v[208:211], v[46:49]
	v_mfma_f32_16x16x32_bf16 v[38:41], v[176:179], v[208:211], v[38:41]
	v_mfma_f32_16x16x32_bf16 v[30:33], v[158:161], v[228:231], v[30:33]
	v_mfma_f32_16x16x32_bf16 v[22:25], v[176:179], v[228:231], v[22:25]
	v_mfma_f32_16x16x32_bf16 v[14:17], v[158:161], v[236:239], v[14:17]
	v_mfma_f32_16x16x32_bf16 v[6:9], v[176:179], v[236:239], v[6:9]
	v_mfma_f32_16x16x32_bf16 v[58:61], v[180:183], v[196:199], v[58:61]
	v_mfma_f32_16x16x32_bf16 v[50:53], v[188:191], v[196:199], v[50:53]
	v_mfma_f32_16x16x32_bf16 v[42:45], v[180:183], v[204:207], v[42:45]
	v_mfma_f32_16x16x32_bf16 v[34:37], v[188:191], v[204:207], v[34:37]
	v_mfma_f32_16x16x32_bf16 v[26:29], v[180:183], v[224:227], v[26:29]
	v_mfma_f32_16x16x32_bf16 v[18:21], v[188:191], v[224:227], v[18:21]
	v_mfma_f32_16x16x32_bf16 v[10:13], v[180:183], v[232:235], v[10:13]
	v_mfma_f32_16x16x32_bf16 v[2:5], v[188:191], v[232:235], v[2:5]
	v_mfma_f32_16x16x32_bf16 v[58:61], v[184:187], v[200:203], v[58:61]
	v_mfma_f32_16x16x32_bf16 v[50:53], v[192:195], v[200:203], v[50:53]
	v_mfma_f32_16x16x32_bf16 v[42:45], v[184:187], v[208:211], v[42:45]
	v_mfma_f32_16x16x32_bf16 v[34:37], v[192:195], v[208:211], v[34:37]
	v_mfma_f32_16x16x32_bf16 v[26:29], v[184:187], v[228:231], v[26:29]
	v_mfma_f32_16x16x32_bf16 v[18:21], v[192:195], v[228:231], v[18:21]
	v_mfma_f32_16x16x32_bf16 v[10:13], v[184:187], v[236:239], v[10:13]
	v_mfma_f32_16x16x32_bf16 v[2:5], v[192:195], v[236:239], v[2:5]
	s_setprio 0
	s_barrier
	s_cmp_gt_u32 s73, 29
	s_cbranch_scc0 .LBB0_432
	s_and_b64 vcc, exec, s[24:25]
	s_cbranch_vccz .LBB0_435
	s_barrier
